# write-through (sc1) stores also for the weight transposes, prep and mix phases
# speedup vs baseline: 1.0050x; 1.0050x over previous
; __device__ __forceinline__ void tr_load(const TrItem& t, int lane, float (&v)[32]) {
;   const int nblk = t.N / 32, kb = t.item / nblk, nb = t.item % nblk, k0 = 64 * kb, n0 = 32 * nb;
;   const float* p = t.W + (size_t)(k0 + (lane >> 5)) * t.N + n0 + (lane & 31);
; #pragma unroll
;   for (int i = 0; i < 32; ++i) v[i] = __builtin_nontemporal_load(p + (size_t)(2 * i) * t.N);
.LBB0_117:
	s_or_b64 exec, exec, s[48:49]
	v_lshrrev_b32_e32 v18, 5, v25
	v_cvt_f32_u32_e32 v19, v18
	v_sub_u32_e32 v35, 0, v18
	v_sub_u32_e32 v34, 0, v3
	v_max_i32_e32 v34, v3, v34
	v_rcp_iflag_f32_e32 v19, v19
	v_ashrrev_i32_e32 v24, 31, v3
	v_lshlrev_b32_e32 v192, 3, v25
	v_lshlrev_b64 v[12:13], 1, v[12:13]
	v_mul_f32_e32 v19, 0x4f7ffffe, v19
	v_cvt_u32_f32_e32 v19, v19
	v_mul_lo_u32 v35, v35, v19
	v_mul_hi_u32 v35, v19, v35
	v_add_u32_e32 v19, v19, v35
	v_mul_hi_u32 v19, v34, v19
	v_mul_lo_u32 v35, v19, v18
	v_sub_u32_e32 v34, v34, v35
	v_add_u32_e32 v36, 1, v19
	v_sub_u32_e32 v35, v34, v18
	v_cmp_ge_u32_e64 s[0:1], v34, v18
	s_nop 1
	v_cndmask_b32_e64 v19, v19, v36, s[0:1]
	v_cndmask_b32_e64 v34, v34, v35, s[0:1]
	v_add_u32_e32 v35, 1, v19
	v_cmp_ge_u32_e64 s[0:1], v34, v18
	s_nop 1
	v_cndmask_b32_e64 v19, v19, v35, s[0:1]
	v_xor_b32_e32 v19, v19, v24
	v_sub_u32_e32 v19, v19, v24
	v_mul_lo_u32 v18, v19, v18
	v_lshlrev_b32_e32 v24, 6, v19
	v_sub_u32_e32 v3, v3, v18
	v_lshlrev_b32_e32 v18, 5, v3
	v_or_b32_e32 v3, v24, v26
	v_mad_i64_i32 v[34:35], s[0:1], v3, v25, 0
	v_lshl_add_u64 v[16:17], v[34:35], 2, v[16:17]
	v_ashrrev_i32_e32 v19, 31, v18
	v_lshl_add_u64 v[16:17], v[18:19], 2, v[16:17]
	v_mov_b32_e32 v3, v193
	v_lshl_add_u64 v[16:17], v[16:17], 0, v[2:3]
	v_lshl_add_u64 v[34:35], v[16:17], 0, v[192:193]
	v_lshl_add_u64 v[36:37], v[34:35], 0, v[192:193]
	v_lshl_add_u64 v[38:39], v[36:37], 0, v[192:193]
	v_lshl_add_u64 v[40:41], v[38:39], 0, v[192:193]
	v_lshl_add_u64 v[42:43], v[40:41], 0, v[192:193]
	v_lshl_add_u64 v[44:45], v[42:43], 0, v[192:193]
	v_lshl_add_u64 v[46:47], v[44:45], 0, v[192:193]
	global_load_dword v25, v[16:17], off nt
	global_load_dword v64, v[34:35], off nt
	global_load_dword v65, v[36:37], off nt
	global_load_dword v66, v[38:39], off nt
	global_load_dword v67, v[40:41], off nt
	global_load_dword v68, v[42:43], off nt
	global_load_dword v69, v[44:45], off nt
	global_load_dword v70, v[46:47], off nt
	v_lshl_add_u64 v[16:17], v[46:47], 0, v[192:193]
	global_load_dword v71, v[16:17], off nt
	v_lshl_add_u64 v[16:17], v[16:17], 0, v[192:193]
	global_load_dword v72, v[16:17], off nt
	v_lshl_add_u64 v[16:17], v[16:17], 0, v[192:193]
	global_load_dword v73, v[16:17], off nt
	v_lshl_add_u64 v[16:17], v[16:17], 0, v[192:193]
	global_load_dword v74, v[16:17], off nt
	v_lshl_add_u64 v[16:17], v[16:17], 0, v[192:193]
	global_load_dword v75, v[16:17], off nt
	v_lshl_add_u64 v[16:17], v[16:17], 0, v[192:193]
	global_load_dword v76, v[16:17], off nt
	v_lshl_add_u64 v[16:17], v[16:17], 0, v[192:193]
	global_load_dword v77, v[16:17], off nt
	v_lshl_add_u64 v[16:17], v[16:17], 0, v[192:193]
	global_load_dword v78, v[16:17], off nt
	v_lshl_add_u64 v[16:17], v[16:17], 0, v[192:193]
	global_load_dword v79, v[16:17], off nt
	v_lshl_add_u64 v[16:17], v[16:17], 0, v[192:193]
	global_load_dword v80, v[16:17], off nt
	v_lshl_add_u64 v[16:17], v[16:17], 0, v[192:193]
	global_load_dword v81, v[16:17], off nt
	v_lshl_add_u64 v[16:17], v[16:17], 0, v[192:193]
	global_load_dword v82, v[16:17], off nt
	v_lshl_add_u64 v[16:17], v[16:17], 0, v[192:193]
	global_load_dword v83, v[16:17], off nt
	v_lshl_add_u64 v[16:17], v[16:17], 0, v[192:193]
	global_load_dword v84, v[16:17], off nt
	v_lshl_add_u64 v[16:17], v[16:17], 0, v[192:193]
	global_load_dword v85, v[16:17], off nt
	v_lshl_add_u64 v[16:17], v[16:17], 0, v[192:193]
	v_lshrrev_b32_e32 v34, 5, v23
	global_load_dword v86, v[16:17], off nt
	v_lshl_add_u64 v[16:17], v[16:17], 0, v[192:193]
	v_cvt_f32_u32_e32 v35, v34
	global_load_dword v87, v[16:17], off nt
	v_lshl_add_u64 v[16:17], v[16:17], 0, v[192:193]
	global_load_dword v88, v[16:17], off nt
	v_lshl_add_u64 v[16:17], v[16:17], 0, v[192:193]
	global_load_dword v89, v[16:17], off nt
	v_lshl_add_u64 v[16:17], v[16:17], 0, v[192:193]
	global_load_dword v90, v[16:17], off nt
	v_lshl_add_u64 v[16:17], v[16:17], 0, v[192:193]
	v_rcp_iflag_f32_e32 v35, v35
	global_load_dword v91, v[16:17], off nt
	v_lshl_add_u64 v[16:17], v[16:17], 0, v[192:193]
	global_load_dword v92, v[16:17], off nt
	v_lshl_add_u64 v[16:17], v[16:17], 0, v[192:193]
	global_load_dword v93, v[16:17], off nt
	v_lshl_add_u64 v[16:17], v[16:17], 0, v[192:193]
	global_load_dword v94, v[16:17], off nt
	v_mul_f32_e32 v17, 0x4f7ffffe, v35
	v_cvt_u32_f32_e32 v17, v17
	v_sub_u32_e32 v36, 0, v34
	v_sub_u32_e32 v35, 0, v22
	v_max_i32_e32 v35, v22, v35
	v_mul_lo_u32 v36, v36, v17
	v_mul_hi_u32 v36, v17, v36
	v_add_u32_e32 v17, v17, v36
	v_mul_hi_u32 v17, v35, v17
	v_mul_lo_u32 v36, v17, v34
	v_sub_u32_e32 v35, v35, v36
	v_add_u32_e32 v36, 1, v17
	v_cmp_ge_u32_e64 s[0:1], v35, v34
	v_ashrrev_i32_e32 v16, 31, v22
	v_lshlrev_b32_e32 v192, 3, v23
	v_cndmask_b32_e64 v17, v17, v36, s[0:1]
	v_sub_u32_e32 v36, v35, v34
	v_cndmask_b32_e64 v35, v35, v36, s[0:1]
	v_add_u32_e32 v36, 1, v17
	v_cmp_ge_u32_e64 s[0:1], v35, v34
	v_mul_lo_u32 v19, v8, v19
	s_nop 0
	v_cndmask_b32_e64 v17, v17, v36, s[0:1]
	v_xor_b32_e32 v17, v17, v16
	v_sub_u32_e32 v16, v17, v16
	v_mul_lo_u32 v17, v16, v34
	v_sub_u32_e32 v17, v22, v17
	v_lshlrev_b32_e32 v22, 6, v16
	v_lshlrev_b32_e32 v16, 5, v17
	v_or_b32_e32 v17, v22, v26
	v_mad_i64_i32 v[34:35], s[0:1], v17, v23, 0
	v_lshl_add_u64 v[20:21], v[34:35], 2, v[20:21]
	v_ashrrev_i32_e32 v17, 31, v16
	v_lshl_add_u64 v[20:21], v[16:17], 2, v[20:21]
	v_lshl_add_u64 v[20:21], v[20:21], 0, v[2:3]
	v_lshl_add_u64 v[34:35], v[20:21], 0, v[192:193]
	v_lshl_add_u64 v[36:37], v[34:35], 0, v[192:193]
	v_lshl_add_u64 v[38:39], v[36:37], 0, v[192:193]
	v_lshl_add_u64 v[40:41], v[38:39], 0, v[192:193]
	v_lshl_add_u64 v[42:43], v[40:41], 0, v[192:193]
	v_lshl_add_u64 v[44:45], v[42:43], 0, v[192:193]
; #define LAS __attribute__((address_space(3)))
; __device__ __forceinline__ unsigned cvt_pk_bf16(float lo, float hi) { f32x2_t v = {lo, hi}; bf16x2_t r = __builtin_convertvector(v, bf16x2_t); return __builtin_bit_cast(unsigned, r); }
; __device__ __forceinline__ void tr_load(const TrItem& t, int lane, float (&v)[32]) {
;     ...
;   const float* p = t.W + (size_t)(k0 + (lane >> 5)) * t.N + n0 + (lane & 31);
; #pragma unroll
;   for (int i = 0; i < 32; ++i) v[i] = __builtin_nontemporal_load(p + (size_t)(2 * i) * t.N);
; __device__ __forceinline__ void tr_finish(const TrItem& t, int lane, const float (&v)[32], LAS float* scr) {
;     ...
;   for (int i = 0; i < 32; ++i) scr[(2 * i + (lane >> 5)) * 33 + (lane & 31)] = v[i];
;   asm volatile("s_waitcnt lgkmcnt(0)" ::: "memory");
;   const int c = lane & 7;
; #pragma unroll
;   for (int j = 0; j < 4; ++j) { const int n = (lane >> 3) + 8 * j; const LAS float* sp = scr + (8 * c) * 33 + n;
;     u32x4 o; o.x = cvt_pk_bf16(sp[0 * 33], sp[1 * 33]); o.y = cvt_pk_bf16(sp[2 * 33], sp[3 * 33]); o.z = cvt_pk_bf16(sp[4 * 33], sp[5 * 33]); o.w = cvt_pk_bf16(sp[6 * 33], sp[7 * 33]);
;     *(u32x4*)(t.WT + (size_t)(n0 + n) * t.ldt + t.koff + k0 + 8 * c) = o; }
	v_lshl_add_u64 v[46:47], v[44:45], 0, v[192:193]
	global_load_dword v3, v[20:21], off nt
	s_nop 0
	global_load_dword v20, v[34:35], off nt
	global_load_dword v21, v[36:37], off nt
	global_load_dword v23, v[38:39], off nt
	s_nop 0
	global_load_dword v34, v[40:41], off nt
	global_load_dword v35, v[42:43], off nt
	global_load_dword v36, v[44:45], off nt
	global_load_dword v37, v[46:47], off nt
	v_lshl_add_u64 v[40:41], v[46:47], 0, v[192:193]
	global_load_dword v38, v[40:41], off nt
	v_lshl_add_u64 v[40:41], v[40:41], 0, v[192:193]
	v_lshl_add_u64 v[42:43], v[40:41], 0, v[192:193]
	global_load_dword v39, v[40:41], off nt
	s_nop 0
	global_load_dword v40, v[42:43], off nt
	v_lshl_add_u64 v[42:43], v[42:43], 0, v[192:193]
	v_lshl_add_u64 v[44:45], v[42:43], 0, v[192:193]
	global_load_dword v41, v[42:43], off nt
	s_nop 0
	global_load_dword v42, v[44:45], off nt
	v_lshl_add_u64 v[44:45], v[44:45], 0, v[192:193]
	v_lshl_add_u64 v[46:47], v[44:45], 0, v[192:193]
	global_load_dword v43, v[44:45], off nt
	s_nop 0
	global_load_dword v44, v[46:47], off nt
	v_lshl_add_u64 v[46:47], v[46:47], 0, v[192:193]
	v_lshl_add_u64 v[48:49], v[46:47], 0, v[192:193]
	global_load_dword v45, v[46:47], off nt
	s_nop 0
	global_load_dword v46, v[48:49], off nt
	v_lshl_add_u64 v[48:49], v[48:49], 0, v[192:193]
	v_lshl_add_u64 v[50:51], v[48:49], 0, v[192:193]
	global_load_dword v47, v[48:49], off nt
	s_nop 0
	global_load_dword v48, v[50:51], off nt
	v_lshl_add_u64 v[50:51], v[50:51], 0, v[192:193]
	v_lshl_add_u64 v[52:53], v[50:51], 0, v[192:193]
	global_load_dword v49, v[50:51], off nt
	s_nop 0
	global_load_dword v50, v[52:53], off nt
	v_lshl_add_u64 v[52:53], v[52:53], 0, v[192:193]
	v_lshl_add_u64 v[54:55], v[52:53], 0, v[192:193]
	global_load_dword v51, v[52:53], off nt
	s_nop 0
	global_load_dword v52, v[54:55], off nt
	v_lshl_add_u64 v[54:55], v[54:55], 0, v[192:193]
	v_lshl_add_u64 v[56:57], v[54:55], 0, v[192:193]
	global_load_dword v53, v[54:55], off nt
	s_nop 0
	global_load_dword v54, v[56:57], off nt
	v_lshl_add_u64 v[56:57], v[56:57], 0, v[192:193]
	v_lshl_add_u64 v[58:59], v[56:57], 0, v[192:193]
	global_load_dword v55, v[56:57], off nt
	s_nop 0
	global_load_dword v56, v[58:59], off nt
	v_lshl_add_u64 v[58:59], v[58:59], 0, v[192:193]
	v_lshl_add_u64 v[60:61], v[58:59], 0, v[192:193]
	global_load_dword v57, v[58:59], off nt
	s_nop 0
	global_load_dword v58, v[60:61], off nt
	v_lshl_add_u64 v[60:61], v[60:61], 0, v[192:193]
	v_lshl_add_u64 v[62:63], v[60:61], 0, v[192:193]
	global_load_dword v59, v[60:61], off nt
	s_nop 0
	global_load_dword v60, v[62:63], off nt
	v_lshl_add_u64 v[62:63], v[62:63], 0, v[192:193]
	global_load_dword v61, v[62:63], off nt
	v_add_u32_e32 v62, 0x400, v33
	s_waitcnt vmcnt(62)
	ds_write2_b32 v33, v25, v64 offset1:66
	s_waitcnt vmcnt(60)
	ds_write2_b32 v33, v65, v66 offset0:132 offset1:198
	s_waitcnt vmcnt(58)
	ds_write2_b32 v62, v67, v68 offset0:8 offset1:74
	s_waitcnt vmcnt(56)
	ds_write2_b32 v62, v69, v70 offset0:140 offset1:206
	v_add_u32_e32 v63, 0x800, v33
	v_add_u32_e32 v64, 0xc00, v33
	v_add_u32_e32 v65, 0x1000, v33
	v_add_u32_e32 v66, 0x1400, v33
	v_add_u32_e32 v67, 0x1800, v33
	v_add_u32_e32 v68, 0x1c00, v33
	s_waitcnt vmcnt(54)
	ds_write2_b32 v63, v71, v72 offset0:16 offset1:82
	s_waitcnt vmcnt(52)
	ds_write2_b32 v63, v73, v74 offset0:148 offset1:214
	s_waitcnt vmcnt(50)
	ds_write2_b32 v64, v75, v76 offset0:24 offset1:90
	s_waitcnt vmcnt(48)
	ds_write2_b32 v64, v77, v78 offset0:156 offset1:222
	s_waitcnt vmcnt(46)
	ds_write2_b32 v65, v79, v80 offset0:32 offset1:98
	s_waitcnt vmcnt(44)
	ds_write2_b32 v65, v81, v82 offset0:164 offset1:230
	s_waitcnt vmcnt(42)
	ds_write2_b32 v66, v83, v84 offset0:40 offset1:106
	s_waitcnt vmcnt(40)
	ds_write2_b32 v66, v85, v86 offset0:172 offset1:238
	s_waitcnt vmcnt(38)
	ds_write2_b32 v67, v87, v88 offset0:48 offset1:114
	s_waitcnt vmcnt(36)
	ds_write2_b32 v67, v89, v90 offset0:180 offset1:246
	s_waitcnt vmcnt(34)
	ds_write2_b32 v68, v91, v92 offset0:56 offset1:122
	s_waitcnt vmcnt(32)
	ds_write2_b32 v68, v93, v94 offset0:188 offset1:254
	s_waitcnt lgkmcnt(0)
	ds_read2_b32 v[74:75], v28 offset0:33 offset1:41
	ds_read2_b32 v[76:77], v28 offset1:8
	ds_read2_b32 v[78:79], v28 offset0:66 offset1:74
	ds_read2_b32 v[80:81], v28 offset0:99 offset1:107
	ds_read2_b32 v[82:83], v28 offset0:132 offset1:140
	ds_read2_b32 v[84:85], v28 offset0:165 offset1:173
	ds_read2_b32 v[86:87], v28 offset0:198 offset1:206
	ds_read2_b32 v[88:89], v28 offset0:231 offset1:239
	v_or_b32_e32 v69, v18, v27
	s_waitcnt lgkmcnt(6)
	v_cvt_pk_bf16_f32 v70, v76, v74
	v_mul_lo_u32 v74, v9, v69
	v_mad_u64_u32 v[90:91], s[0:1], v8, v69, 0
	v_add3_u32 v91, v91, v19, v74
	v_ashrrev_i32_e32 v25, 31, v24
	v_lshl_add_u64 v[90:91], v[90:91], 1, v[10:11]
	v_lshl_add_u64 v[90:91], v[90:91], 0, v[12:13]
	v_lshlrev_b64 v[24:25], 1, v[24:25]
	v_lshl_add_u64 v[90:91], v[90:91], 0, v[24:25]
	v_lshlrev_b32_e32 v192, 1, v0
	s_waitcnt lgkmcnt(4)
	v_cvt_pk_bf16_f32 v71, v78, v80
	s_waitcnt lgkmcnt(2)
	v_cvt_pk_bf16_f32 v72, v82, v84
	s_waitcnt lgkmcnt(0)
	v_cvt_pk_bf16_f32 v73, v86, v88
	v_lshl_add_u64 v[90:91], v[90:91], 0, v[192:193]
	v_or_b32_e32 v69, v18, v29
	global_store_dwordx4 v[90:91], v[70:73], off sc1
	v_mul_lo_u32 v76, v9, v69
	s_nop 0
	v_cvt_pk_bf16_f32 v70, v77, v75
	v_mad_u64_u32 v[74:75], s[0:1], v8, v69, 0
	v_add3_u32 v75, v75, v19, v76
	v_lshl_add_u64 v[74:75], v[74:75], 1, v[10:11]
	v_lshl_add_u64 v[74:75], v[74:75], 0, v[12:13]
	v_lshl_add_u64 v[74:75], v[74:75], 0, v[24:25]
	v_cvt_pk_bf16_f32 v71, v79, v81
	v_cvt_pk_bf16_f32 v72, v83, v85
	v_cvt_pk_bf16_f32 v73, v87, v89
	v_lshl_add_u64 v[74:75], v[74:75], 0, v[192:193]
	ds_read2_b32 v[76:77], v28 offset0:16 offset1:24
	ds_read2_b32 v[78:79], v28 offset0:49 offset1:57
	ds_read2_b32 v[80:81], v28 offset0:82 offset1:90
	ds_read2_b32 v[82:83], v28 offset0:115 offset1:123
	ds_read2_b32 v[84:85], v28 offset0:148 offset1:156
	ds_read2_b32 v[86:87], v28 offset0:181 offset1:189
	ds_read2_b32 v[88:89], v28 offset0:214 offset1:222
	ds_read2_b32 v[90:91], v28 offset0:247 offset1:255
	v_or_b32_e32 v69, v18, v30
	global_store_dwordx4 v[74:75], v[70:73], off sc1
	v_mad_u64_u32 v[74:75], s[0:1], v8, v69, 0
	s_waitcnt lgkmcnt(6)
; #define LAS __attribute__((address_space(3)))
; __device__ __forceinline__ unsigned cvt_pk_bf16(float lo, float hi) { f32x2_t v = {lo, hi}; bf16x2_t r = __builtin_convertvector(v, bf16x2_t); return __builtin_bit_cast(unsigned, r); }
; __device__ __forceinline__ void tr_finish(const TrItem& t, int lane, const float (&v)[32], LAS float* scr) {
;     ...
;   for (int i = 0; i < 32; ++i) scr[(2 * i + (lane >> 5)) * 33 + (lane & 31)] = v[i];
;   asm volatile("s_waitcnt lgkmcnt(0)" ::: "memory");
;   const int c = lane & 7;
; #pragma unroll
;   for (int j = 0; j < 4; ++j) { const int n = (lane >> 3) + 8 * j; const LAS float* sp = scr + (8 * c) * 33 + n;
;     u32x4 o; o.x = cvt_pk_bf16(sp[0 * 33], sp[1 * 33]); o.y = cvt_pk_bf16(sp[2 * 33], sp[3 * 33]); o.z = cvt_pk_bf16(sp[4 * 33], sp[5 * 33]); o.w = cvt_pk_bf16(sp[6 * 33], sp[7 * 33]);
;     *(u32x4*)(t.WT + (size_t)(n0 + n) * t.ldt + t.koff + k0 + 8 * c) = o; }
;   asm volatile("s_waitcnt lgkmcnt(0)" ::: "memory");
; __global__ void __launch_bounds__(512) mega(Args a) {
;     ...
;           if (h1) tr_finish(T1, lane, v1, scr);
	v_cvt_pk_bf16_f32 v70, v76, v78
	v_mul_lo_u32 v76, v9, v69
	v_or_b32_e32 v18, v18, v31
	v_add3_u32 v75, v75, v19, v76
	v_mul_lo_u32 v69, v9, v18
	v_mad_u64_u32 v[8:9], s[0:1], v8, v18, 0
	v_lshl_add_u64 v[74:75], v[74:75], 1, v[10:11]
	v_add3_u32 v9, v9, v19, v69
	v_lshl_add_u64 v[74:75], v[74:75], 0, v[12:13]
	v_lshl_add_u64 v[8:9], v[8:9], 1, v[10:11]
	v_lshl_add_u64 v[74:75], v[74:75], 0, v[24:25]
	v_lshl_add_u64 v[8:9], v[8:9], 0, v[12:13]
	s_waitcnt lgkmcnt(4)
	v_cvt_pk_bf16_f32 v71, v80, v82
	s_waitcnt lgkmcnt(2)
	v_cvt_pk_bf16_f32 v72, v84, v86
	s_waitcnt lgkmcnt(0)
	v_cvt_pk_bf16_f32 v73, v88, v90
	v_lshl_add_u64 v[74:75], v[74:75], 0, v[192:193]
	v_lshl_add_u64 v[8:9], v[8:9], 0, v[24:25]
	global_store_dwordx4 v[74:75], v[70:73], off sc1
	v_lshl_add_u64 v[8:9], v[8:9], 0, v[192:193]
	s_nop 0
	v_cvt_pk_bf16_f32 v70, v77, v79
	v_cvt_pk_bf16_f32 v71, v81, v83
	v_cvt_pk_bf16_f32 v72, v85, v87
	v_cvt_pk_bf16_f32 v73, v89, v91
	global_store_dwordx4 v[8:9], v[70:73], off sc1
	s_waitcnt lgkmcnt(0)
	s_and_saveexec_b64 s[0:1], vcc
	s_cbranch_execz .LBB0_88
	s_waitcnt vmcnt(34)
	ds_write2_b32 v33, v3, v20 offset1:66
	s_waitcnt vmcnt(32)
	ds_write2_b32 v33, v21, v23 offset0:132 offset1:198
	s_waitcnt vmcnt(30)
	ds_write2_b32 v62, v34, v35 offset0:8 offset1:74
	s_waitcnt vmcnt(28)
	ds_write2_b32 v62, v36, v37 offset0:140 offset1:206
	s_waitcnt vmcnt(26)
	ds_write2_b32 v63, v38, v39 offset0:16 offset1:82
	s_waitcnt vmcnt(24)
	ds_write2_b32 v63, v40, v41 offset0:148 offset1:214
	s_waitcnt vmcnt(22)
	ds_write2_b32 v64, v42, v43 offset0:24 offset1:90
	s_waitcnt vmcnt(20)
	ds_write2_b32 v64, v44, v45 offset0:156 offset1:222
	s_waitcnt vmcnt(18)
	ds_write2_b32 v65, v46, v47 offset0:32 offset1:98
	s_waitcnt vmcnt(16)
	ds_write2_b32 v65, v48, v49 offset0:164 offset1:230
	s_waitcnt vmcnt(14)
	ds_write2_b32 v66, v50, v51 offset0:40 offset1:106
	s_waitcnt vmcnt(12)
	ds_write2_b32 v66, v52, v53 offset0:172 offset1:238
	s_waitcnt vmcnt(10)
	ds_write2_b32 v67, v54, v55 offset0:48 offset1:114
	s_waitcnt vmcnt(8)
	ds_write2_b32 v67, v56, v57 offset0:180 offset1:246
	s_waitcnt vmcnt(6)
	ds_write2_b32 v68, v58, v59 offset0:56 offset1:122
	s_waitcnt vmcnt(4)
	ds_write2_b32 v68, v60, v61 offset0:188 offset1:254
	s_waitcnt lgkmcnt(0)
	ds_read2_b32 v[12:13], v28 offset0:33 offset1:41
	ds_read2_b32 v[18:19], v28 offset1:8
	ds_read2_b32 v[20:21], v28 offset0:66 offset1:74
	ds_read2_b32 v[24:25], v28 offset0:99 offset1:107
	ds_read2_b32 v[34:35], v28 offset0:132 offset1:140
	ds_read2_b32 v[36:37], v28 offset0:165 offset1:173
	ds_read2_b32 v[38:39], v28 offset0:198 offset1:206
	ds_read2_b32 v[40:41], v28 offset0:231 offset1:239
	v_or_b32_e32 v3, v16, v27
	s_waitcnt lgkmcnt(6)
	v_cvt_pk_bf16_f32 v8, v18, v12
	v_mul_lo_u32 v12, v5, v3
	v_mul_lo_u32 v17, v4, v17
	v_mad_u64_u32 v[42:43], s[22:23], v4, v3, 0
	v_add3_u32 v43, v43, v17, v12
	v_ashrrev_i32_e32 v23, 31, v22
	v_lshl_add_u64 v[42:43], v[42:43], 1, v[14:15]
	v_lshlrev_b64 v[44:45], 1, v[6:7]
	v_lshl_add_u64 v[6:7], v[42:43], 0, v[44:45]
	v_lshlrev_b64 v[22:23], 1, v[22:23]
	v_lshl_add_u64 v[6:7], v[6:7], 0, v[22:23]
	s_waitcnt lgkmcnt(4)
	v_cvt_pk_bf16_f32 v9, v20, v24
	s_waitcnt lgkmcnt(2)
	v_cvt_pk_bf16_f32 v10, v34, v36
	s_waitcnt lgkmcnt(0)
	v_cvt_pk_bf16_f32 v11, v38, v40
	v_lshl_add_u64 v[6:7], v[6:7], 0, v[192:193]
	v_or_b32_e32 v3, v16, v29
	global_store_dwordx4 v[6:7], v[8:11], off sc1
	v_mul_lo_u32 v12, v5, v3
	v_cvt_pk_bf16_f32 v6, v19, v13
	v_mad_u64_u32 v[10:11], s[22:23], v4, v3, 0
	v_add3_u32 v11, v11, v17, v12
	v_lshl_add_u64 v[10:11], v[10:11], 1, v[14:15]
	v_lshl_add_u64 v[10:11], v[10:11], 0, v[44:45]
	v_lshl_add_u64 v[10:11], v[10:11], 0, v[22:23]
	v_cvt_pk_bf16_f32 v7, v21, v25
	v_cvt_pk_bf16_f32 v8, v35, v37
	v_cvt_pk_bf16_f32 v9, v39, v41
	v_lshl_add_u64 v[10:11], v[10:11], 0, v[192:193]
	ds_read2_b32 v[12:13], v28 offset0:16 offset1:24
	ds_read2_b32 v[18:19], v28 offset0:49 offset1:57
	ds_read2_b32 v[20:21], v28 offset0:82 offset1:90
	ds_read2_b32 v[24:25], v28 offset0:115 offset1:123
	ds_read2_b32 v[34:35], v28 offset0:148 offset1:156
	ds_read2_b32 v[36:37], v28 offset0:181 offset1:189
	ds_read2_b32 v[38:39], v28 offset0:214 offset1:222
	ds_read2_b32 v[40:41], v28 offset0:247 offset1:255
	v_or_b32_e32 v3, v16, v30
	global_store_dwordx4 v[10:11], v[6:9], off sc1
	v_mad_u64_u32 v[10:11], s[22:23], v4, v3, 0
	s_waitcnt lgkmcnt(6)
	v_cvt_pk_bf16_f32 v6, v12, v18
	v_mul_lo_u32 v12, v5, v3
	v_add3_u32 v11, v11, v17, v12
	v_lshl_add_u64 v[10:11], v[10:11], 1, v[14:15]
	v_lshl_add_u64 v[10:11], v[10:11], 0, v[44:45]
	v_lshl_add_u64 v[10:11], v[10:11], 0, v[22:23]
	s_waitcnt lgkmcnt(4)
	v_cvt_pk_bf16_f32 v7, v20, v24
	s_waitcnt lgkmcnt(2)
	v_cvt_pk_bf16_f32 v8, v34, v36
	s_waitcnt lgkmcnt(0)
	v_cvt_pk_bf16_f32 v9, v38, v40
	v_lshl_add_u64 v[10:11], v[10:11], 0, v[192:193]
	v_or_b32_e32 v3, v16, v31
	global_store_dwordx4 v[10:11], v[6:9], off sc1
	v_mul_lo_u32 v10, v5, v3
	v_mad_u64_u32 v[4:5], s[22:23], v4, v3, 0
	v_add3_u32 v5, v5, v17, v10
	v_lshl_add_u64 v[4:5], v[4:5], 1, v[14:15]
	v_lshl_add_u64 v[4:5], v[4:5], 0, v[44:45]
	v_lshl_add_u64 v[4:5], v[4:5], 0, v[22:23]
	v_cvt_pk_bf16_f32 v6, v13, v19
	v_cvt_pk_bf16_f32 v7, v21, v25
	v_cvt_pk_bf16_f32 v8, v35, v37
	v_cvt_pk_bf16_f32 v9, v39, v41
	v_lshl_add_u64 v[4:5], v[4:5], 0, v[192:193]
	global_store_dwordx4 v[4:5], v[6:9], off sc1
	s_waitcnt lgkmcnt(0)
	s_branch .LBB0_88

; __device__ __forceinline__ unsigned cvt_pk_bf16(float lo, float hi) { f32x2_t v = {lo, hi}; bf16x2_t r = __builtin_convertvector(v, bf16x2_t); return __builtin_bit_cast(unsigned, r); }
; __device__ __forceinline__ float bf_lo(unsigned w) { return __uint_as_float(w << 16); }
; __device__ __forceinline__ float bf_hi(unsigned w) { return __uint_as_float(w & 0xffff0000u); }
; __global__ void __launch_bounds__(512) mega(Args a) {
;     ...
;         auto mix_load = [&](const int tok) { MixIn m;
;           m.l0 = LSE[((size_t)0 * MT + tok) * 4 + hg]; m.l1 = LSE[((size_t)1 * MT + tok) * 4 + hg]; m.l2 = LSE[((size_t)2 * MT + tok) * 4 + hg];
;           m.o0 = __builtin_nontemporal_load((const u32x4*)(OC + ((size_t)0 * MT + tok) * 512 + hg * 128 + e8)); m.o1 = __builtin_nontemporal_load((const u32x4*)(OC + ((size_t)1 * MT + tok) * 512 + hg * 128 + e8));
;           m.o2 = __builtin_nontemporal_load((const u32x4*)(OC + ((size_t)2 * MT + tok) * 512 + hg * 128 + e8)); m.z = *(const u32x4*)(PROJ + (size_t)tok * NIN + C_ZC + hg * 128 + e8); return m; };
;         auto mix_item = [&](const int tok, const MixIn& m) {
;           const float mx = fmaxf(m.l0, fmaxf(m.l1, m.l2)), e0 = __expf(m.l0 - mx), e1 = __expf(m.l1 - mx), e2 = __expf(m.l2 - mx), inv = 1.f / (e0 + e1 + e2);
;           const float w0 = e0 * inv, w1 = e1 * inv, w2 = e2 * inv;
;           u32x4 w;
; #pragma unroll
;           for (int q = 0; q < 4; ++q) { const float lo = (w0 * bf_lo(m.o0[q]) + w1 * bf_lo(m.o1[q]) + w2 * bf_lo(m.o2[q])) * bf_lo(m.z[q]), hi_ = (w0 * bf_hi(m.o0[q]) + w1 * bf_hi(m.o1[q]) + w2 * bf_hi(m.o2[q])) * bf_hi(m.z[q]); w[q] = cvt_pk_bf16(lo, hi_); }
;           *(u32x4*)(Y + (size_t)tok * YW + 2048 + hg * 128 + e8) = w; };
;         int tok0 = gw;
;         for (; tok0 + 3 * NGW < MT; tok0 += 4 * NGW) {
;           const MixIn m0 = mix_load(tok0), m1 = mix_load(tok0 + NGW), m2 = mix_load(tok0 + 2 * NGW), m3 = mix_load(tok0 + 3 * NGW);
;           mix_item(tok0, m0); mix_item(tok0 + NGW, m1); mix_item(tok0 + 2 * NGW, m2); mix_item(tok0 + 3 * NGW, m3);
.LBB0_190:
	v_lshl_add_u64 v[0:1], v[86:87], 0, s[28:29]
	v_add_co_u32_e32 v2, vcc, 0x48000000, v0
	s_brev_b32 s11, 18
	s_nop 0
	v_addc_co_u32_e32 v3, vcc, 0, v1, vcc
	global_load_dword v102, v[2:3], off
	v_add_co_u32_e32 v2, vcc, 0x48040000, v0
	v_add_u32_e32 v92, s3, v64
	s_nop 0
	v_addc_co_u32_e32 v3, vcc, 0, v1, vcc
	v_add_co_u32_e32 v0, vcc, 0x48080000, v0
	global_load_dword v104, v[2:3], off
	s_nop 0
	v_addc_co_u32_e32 v1, vcc, 0, v1, vcc
	global_load_dword v105, v[0:1], off
	v_lshl_add_u64 v[0:1], v[84:85], 0, s[28:29]
	v_add_co_u32_e32 v2, vcc, 0x45000000, v0
	v_ashrrev_i32_e32 v93, 31, v92
	s_nop 0
	v_addc_co_u32_e32 v3, vcc, 0, v1, vcc
	global_load_dwordx4 v[48:51], v[2:3], off nt
	v_add_co_u32_e32 v2, vcc, 0x46000000, v0
	v_mov_b64_e32 v[12:13], s[8:9]
	s_nop 0
	v_addc_co_u32_e32 v3, vcc, 0, v1, vcc
	global_load_dwordx4 v[52:55], v[2:3], off nt
	v_add_co_u32_e32 v0, vcc, 0x47000000, v0
	v_mov_b32_e32 v89, v193
	s_nop 0
	v_addc_co_u32_e32 v1, vcc, 0, v1, vcc
	global_load_dwordx4 v[56:59], v[0:1], off nt
	v_lshl_add_u64 v[0:1], v[82:83], 0, s[28:29]
	global_load_dwordx4 v[60:63], v[0:1], off
	v_lshl_add_u64 v[0:1], v[78:79], 0, s[28:29]
	v_add_co_u32_e32 v2, vcc, s11, v0
	s_mov_b32 s11, 0x48040000
	s_nop 0
	v_addc_co_u32_e32 v3, vcc, 0, v1, vcc
	global_load_dword v99, v[2:3], off
	v_add_co_u32_e32 v2, vcc, s11, v0
	s_mov_b32 s11, 0x48080000
	s_nop 0
	v_addc_co_u32_e32 v3, vcc, 0, v1, vcc
	v_add_co_u32_e32 v0, vcc, s11, v0
	global_load_dword v100, v[2:3], off
	s_nop 0
	v_addc_co_u32_e32 v1, vcc, 0, v1, vcc
	global_load_dword v101, v[0:1], off
	v_lshl_add_u64 v[0:1], v[76:77], 0, s[28:29]
	s_mov_b32 s11, 0x45000000
	v_add_co_u32_e32 v2, vcc, s11, v0
	s_mov_b32 s11, 0x46000000
	s_nop 0
	v_addc_co_u32_e32 v3, vcc, 0, v1, vcc
	global_load_dwordx4 v[32:35], v[2:3], off nt
	v_add_co_u32_e32 v2, vcc, s11, v0
	s_mov_b32 s11, 0x47000000
	s_nop 0
	v_addc_co_u32_e32 v3, vcc, 0, v1, vcc
	v_add_co_u32_e32 v0, vcc, s11, v0
	global_load_dwordx4 v[36:39], v[2:3], off nt
	s_nop 0
	v_addc_co_u32_e32 v1, vcc, 0, v1, vcc
	global_load_dwordx4 v[40:43], v[0:1], off nt
	v_lshl_add_u64 v[0:1], v[74:75], 0, s[28:29]
	global_load_dwordx4 v[44:47], v[0:1], off
	v_lshl_add_u64 v[0:1], v[92:93], 4, v[68:69]
	global_load_dword v96, v[0:1], off
	v_lshl_add_u64 v[0:1], v[92:93], 0, s[22:23]
	v_lshl_add_u64 v[2:3], v[0:1], 4, v[68:69]
	v_lshlrev_b64 v[0:1], 10, v[0:1]
	v_lshl_add_u64 v[0:1], v[70:71], 0, v[0:1]
	global_load_dword v97, v[2:3], off
	global_load_dwordx4 v[24:27], v[0:1], off nt
	v_lshl_add_u64 v[2:3], v[92:93], 0, s[24:25]
	v_lshlrev_b64 v[0:1], 10, v[2:3]
	v_lshl_add_u64 v[4:5], v[2:3], 4, v[68:69]
	v_lshl_add_u64 v[0:1], v[70:71], 0, v[0:1]
	global_load_dword v98, v[4:5], off
	global_load_dwordx4 v[20:23], v[0:1], off nt
	v_mad_i64_i32 v[0:1], s[16:17], v92, s14, v[12:13]
	v_lshl_add_u64 v[0:1], v[0:1], 0, v[192:193]
	v_lshl_add_u64 v[0:1], v[0:1], 0, v[88:89]
	v_add_u32_e32 v90, s2, v64
	v_add_co_u32_e32 v0, vcc, s19, v0
	v_lshlrev_b64 v[4:5], 10, v[92:93]
	s_nop 0
	v_addc_co_u32_e32 v1, vcc, 0, v1, vcc
	v_ashrrev_i32_e32 v91, 31, v90
	v_lshl_add_u64 v[4:5], v[70:71], 0, v[4:5]
	global_load_dwordx4 v[28:31], v[0:1], off offset:2048
	v_lshl_add_u64 v[0:1], v[90:91], 4, v[68:69]
	global_load_dwordx4 v[16:19], v[4:5], off nt
	global_load_dword v65, v[0:1], off
	v_lshl_add_u64 v[4:5], v[90:91], 0, s[22:23]
	v_lshl_add_u64 v[0:1], v[4:5], 4, v[68:69]
	v_lshlrev_b64 v[4:5], 10, v[4:5]
	v_lshl_add_u64 v[6:7], v[90:91], 0, s[24:25]
	v_lshl_add_u64 v[4:5], v[70:71], 0, v[4:5]
	global_load_dword v67, v[0:1], off
	global_load_dwordx4 v[8:11], v[4:5], off nt
	v_lshlrev_b64 v[4:5], 10, v[6:7]
	v_lshl_add_u64 v[0:1], v[6:7], 4, v[68:69]
	v_lshl_add_u64 v[4:5], v[70:71], 0, v[4:5]
	global_load_dword v93, v[0:1], off
	v_mad_i64_i32 v[12:13], s[16:17], v90, s14, v[12:13]
	global_load_dwordx4 v[4:7], v[4:5], off nt
	v_lshlrev_b64 v[0:1], 10, v[90:91]
	s_waitcnt vmcnt(0)
	v_max3_f32 v91, v102, v104, v105
	v_sub_f32_e32 v102, v102, v91
	v_mul_f32_e32 v102, 0x3fb8aa3b, v102
	v_exp_f32_e32 v103, v102
	v_sub_f32_e32 v102, v104, v91
	v_mul_f32_e32 v102, 0x3fb8aa3b, v102
	v_sub_f32_e32 v91, v105, v91
	v_exp_f32_e32 v102, v102
	v_mul_f32_e32 v91, 0x3fb8aa3b, v91
	v_exp_f32_e32 v91, v91
	v_lshl_add_u64 v[12:13], v[12:13], 0, v[192:193]
	v_add_f32_e32 v104, v103, v102
	v_lshl_add_u64 v[12:13], v[12:13], 0, v[88:89]
	v_add_f32_e32 v104, v91, v104
	v_div_scale_f32 v105, s[16:17], v104, v104, 1.0
	v_rcp_f32_e32 v106, v105
	v_add_co_u32_e32 v12, vcc, s19, v12
	v_lshlrev_b32_e32 v110, 16, v56
	s_nop 0
	v_addc_co_u32_e32 v13, vcc, 0, v13, vcc
	v_fma_f32 v107, -v105, v106, 1.0
	v_fmac_f32_e32 v106, v107, v106
	v_div_scale_f32 v107, vcc, 1.0, v104, 1.0
	v_mul_f32_e32 v108, v107, v106
	v_fma_f32 v109, -v105, v108, v107
	v_fmac_f32_e32 v108, v109, v106
	v_fma_f32 v105, -v105, v108, v107
	v_div_fmas_f32 v105, v105, v106, v108
	v_div_fixup_f32 v104, v105, v104, 1.0
	v_pk_mul_f32 v[102:103], v[102:103], v[104:105] op_sel_hi:[1,0]
	v_lshlrev_b32_e32 v108, 16, v48
	v_and_b32_e32 v109, 0xffff0000, v52
	v_mul_f32_e32 v106, v91, v104
	v_lshlrev_b32_e32 v104, 16, v52
	v_and_b32_e32 v105, 0xffff0000, v48
	v_pk_mul_f32 v[108:109], v[102:103], v[108:109] op_sel:[1,0] op_sel_hi:[0,1]
	v_and_b32_e32 v111, 0xffff0000, v56
	v_pk_fma_f32 v[104:105], v[102:103], v[104:105], v[108:109]
	v_lshlrev_b32_e32 v112, 16, v60
	v_and_b32_e32 v113, 0xffff0000, v60
	v_pk_fma_f32 v[104:105], v[106:107], v[110:111], v[104:105] op_sel_hi:[0,1,1]
	v_pk_mul_f32 v[104:105], v[104:105], v[112:113]
	v_lshlrev_b32_e32 v52, 16, v49
	v_cvt_pk_bf16_f32 v48, v104, v105
	v_lshlrev_b32_e32 v104, 16, v53
	v_and_b32_e32 v53, 0xffff0000, v53
; __device__ __forceinline__ unsigned cvt_pk_bf16(float lo, float hi) { f32x2_t v = {lo, hi}; bf16x2_t r = __builtin_convertvector(v, bf16x2_t); return __builtin_bit_cast(unsigned, r); }
; __device__ __forceinline__ float bf_lo(unsigned w) { return __uint_as_float(w << 16); }
; __device__ __forceinline__ float bf_hi(unsigned w) { return __uint_as_float(w & 0xffff0000u); }
; __global__ void __launch_bounds__(512) mega(Args a) {
;     ...
;         auto mix_item = [&](const int tok, const MixIn& m) {
;           const float mx = fmaxf(m.l0, fmaxf(m.l1, m.l2)), e0 = __expf(m.l0 - mx), e1 = __expf(m.l1 - mx), e2 = __expf(m.l2 - mx), inv = 1.f / (e0 + e1 + e2);
;           const float w0 = e0 * inv, w1 = e1 * inv, w2 = e2 * inv;
;           u32x4 w;
; #pragma unroll
;           for (int q = 0; q < 4; ++q) { const float lo = (w0 * bf_lo(m.o0[q]) + w1 * bf_lo(m.o1[q]) + w2 * bf_lo(m.o2[q])) * bf_lo(m.z[q]), hi_ = (w0 * bf_hi(m.o0[q]) + w1 * bf_hi(m.o1[q]) + w2 * bf_hi(m.o2[q])) * bf_hi(m.z[q]); w[q] = cvt_pk_bf16(lo, hi_); }
;           *(u32x4*)(Y + (size_t)tok * YW + 2048 + hg * 128 + e8) = w; };
	v_and_b32_e32 v105, 0xffff0000, v49
	v_pk_mul_f32 v[52:53], v[102:103], v[52:53] op_sel:[1,0] op_sel_hi:[0,1]
	v_lshlrev_b32_e32 v56, 16, v57
	v_and_b32_e32 v57, 0xffff0000, v57
	v_pk_fma_f32 v[52:53], v[102:103], v[104:105], v[52:53]
	v_lshlrev_b32_e32 v60, 16, v61
	v_and_b32_e32 v61, 0xffff0000, v61
	v_pk_fma_f32 v[52:53], v[106:107], v[56:57], v[52:53] op_sel_hi:[0,1,1]
	v_pk_mul_f32 v[52:53], v[52:53], v[60:61]
	v_lshlrev_b32_e32 v56, 16, v50
	v_and_b32_e32 v57, 0xffff0000, v54
	v_cvt_pk_bf16_f32 v49, v52, v53
	v_lshlrev_b32_e32 v52, 16, v54
	v_and_b32_e32 v53, 0xffff0000, v50
	v_pk_mul_f32 v[56:57], v[102:103], v[56:57] op_sel:[1,0] op_sel_hi:[0,1]
	v_lshlrev_b32_e32 v60, 16, v58
	v_and_b32_e32 v61, 0xffff0000, v58
	v_pk_fma_f32 v[52:53], v[102:103], v[52:53], v[56:57]
	v_lshlrev_b32_e32 v104, 16, v62
	v_and_b32_e32 v105, 0xffff0000, v62
	v_pk_fma_f32 v[52:53], v[106:107], v[60:61], v[52:53] op_sel_hi:[0,1,1]
	v_pk_mul_f32 v[52:53], v[52:53], v[104:105]
	v_lshlrev_b32_e32 v54, 16, v51
	v_cvt_pk_bf16_f32 v50, v52, v53
	v_lshlrev_b32_e32 v52, 16, v55
	v_and_b32_e32 v55, 0xffff0000, v55
	v_and_b32_e32 v53, 0xffff0000, v51
	v_pk_mul_f32 v[54:55], v[102:103], v[54:55] op_sel:[1,0] op_sel_hi:[0,1]
	v_pk_fma_f32 v[52:53], v[102:103], v[52:53], v[54:55]
	v_lshlrev_b32_e32 v54, 16, v59
	v_and_b32_e32 v55, 0xffff0000, v59
	v_pk_fma_f32 v[52:53], v[106:107], v[54:55], v[52:53] op_sel_hi:[0,1,1]
	v_lshlrev_b32_e32 v54, 16, v63
	v_and_b32_e32 v55, 0xffff0000, v63
	v_pk_mul_f32 v[52:53], v[52:53], v[54:55]
	v_lshl_add_u64 v[0:1], v[70:71], 0, v[0:1]
	v_cvt_pk_bf16_f32 v51, v52, v53
	v_lshl_add_u64 v[52:53], v[80:81], 0, s[28:29]
	global_load_dwordx4 v[0:3], v[0:1], off nt
	v_and_b32_e32 v57, 0xffff0000, v40
	global_load_dwordx4 v[12:15], v[12:13], off offset:2048
	v_lshlrev_b32_e32 v58, 16, v44
	global_store_dwordx4 v[52:53], v[48:51], off sc1
	v_and_b32_e32 v59, 0xffff0000, v44
	v_lshlrev_b32_e32 v44, 16, v45
	v_max3_f32 v50, v99, v100, v101
	v_sub_f32_e32 v48, v99, v50
	v_mul_f32_e32 v48, 0x3fb8aa3b, v48
	v_exp_f32_e32 v49, v48
	v_sub_f32_e32 v48, v100, v50
	v_mul_f32_e32 v48, 0x3fb8aa3b, v48
	v_sub_f32_e32 v50, v101, v50
	v_exp_f32_e32 v48, v48
	v_mul_f32_e32 v50, 0x3fb8aa3b, v50
	v_exp_f32_e32 v51, v50
	v_and_b32_e32 v45, 0xffff0000, v45
	v_add_f32_e32 v50, v49, v48
	v_add_u32_e32 v64, s36, v64
	v_add_f32_e32 v50, v51, v50
	v_div_scale_f32 v52, s[16:17], v50, v50, 1.0
	v_rcp_f32_e32 v53, v52
	v_lshl_add_u64 v[74:75], v[74:75], 0, s[42:43]
	v_lshl_add_u64 v[76:77], v[76:77], 0, s[44:45]
	v_lshl_add_u64 v[78:79], v[78:79], 0, s[46:47]
	v_fma_f32 v54, -v52, v53, 1.0
	v_fmac_f32_e32 v53, v54, v53
	v_div_scale_f32 v54, vcc, 1.0, v50, 1.0
	v_mul_f32_e32 v55, v54, v53
	v_fma_f32 v56, -v52, v55, v54
	v_fmac_f32_e32 v55, v56, v53
	v_fma_f32 v52, -v52, v55, v54
	v_div_fmas_f32 v52, v52, v53, v55
	v_div_fixup_f32 v50, v52, v50, 1.0
	v_pk_mul_f32 v[48:49], v[48:49], v[50:51] op_sel_hi:[1,0]
	v_lshlrev_b32_e32 v54, 16, v32
	v_and_b32_e32 v55, 0xffff0000, v36
	v_mul_f32_e32 v52, v51, v50
	v_lshlrev_b32_e32 v50, 16, v36
	v_and_b32_e32 v51, 0xffff0000, v32
	v_pk_mul_f32 v[54:55], v[48:49], v[54:55] op_sel:[1,0] op_sel_hi:[0,1]
	v_lshlrev_b32_e32 v56, 16, v40
	v_pk_fma_f32 v[50:51], v[48:49], v[50:51], v[54:55]
	v_lshlrev_b32_e32 v36, 16, v33
	v_pk_fma_f32 v[50:51], v[52:53], v[56:57], v[50:51] op_sel_hi:[0,1,1]
	v_pk_mul_f32 v[50:51], v[50:51], v[58:59]
	v_lshlrev_b32_e32 v40, 16, v41
	v_cvt_pk_bf16_f32 v32, v50, v51
	v_lshlrev_b32_e32 v50, 16, v37
	v_and_b32_e32 v37, 0xffff0000, v37
	v_and_b32_e32 v51, 0xffff0000, v33
	v_pk_mul_f32 v[36:37], v[48:49], v[36:37] op_sel:[1,0] op_sel_hi:[0,1]
	v_and_b32_e32 v41, 0xffff0000, v41
	v_pk_fma_f32 v[36:37], v[48:49], v[50:51], v[36:37]
	v_lshlrev_b32_e32 v50, 16, v46
	v_pk_fma_f32 v[36:37], v[52:53], v[40:41], v[36:37] op_sel_hi:[0,1,1]
	v_pk_mul_f32 v[36:37], v[36:37], v[44:45]
	v_lshlrev_b32_e32 v40, 16, v34
	v_and_b32_e32 v41, 0xffff0000, v38
	v_cvt_pk_bf16_f32 v33, v36, v37
	v_lshlrev_b32_e32 v36, 16, v38
	v_and_b32_e32 v37, 0xffff0000, v34
	v_pk_mul_f32 v[40:41], v[48:49], v[40:41] op_sel:[1,0] op_sel_hi:[0,1]
	v_lshlrev_b32_e32 v44, 16, v42
	v_and_b32_e32 v45, 0xffff0000, v42
	v_pk_fma_f32 v[36:37], v[48:49], v[36:37], v[40:41]
	v_and_b32_e32 v51, 0xffff0000, v46
	v_pk_fma_f32 v[36:37], v[52:53], v[44:45], v[36:37] op_sel_hi:[0,1,1]
	v_pk_mul_f32 v[36:37], v[36:37], v[50:51]
	v_lshlrev_b32_e32 v38, 16, v35
	v_cvt_pk_bf16_f32 v34, v36, v37
	v_lshlrev_b32_e32 v36, 16, v39
	v_and_b32_e32 v39, 0xffff0000, v39
	v_and_b32_e32 v37, 0xffff0000, v35
	v_pk_mul_f32 v[38:39], v[48:49], v[38:39] op_sel:[1,0] op_sel_hi:[0,1]
	v_pk_fma_f32 v[36:37], v[48:49], v[36:37], v[38:39]
	v_lshlrev_b32_e32 v38, 16, v43
	v_and_b32_e32 v39, 0xffff0000, v43
	v_pk_fma_f32 v[36:37], v[52:53], v[38:39], v[36:37] op_sel_hi:[0,1,1]
	v_lshlrev_b32_e32 v38, 16, v47
	v_and_b32_e32 v39, 0xffff0000, v47
	v_pk_mul_f32 v[36:37], v[36:37], v[38:39]
	v_and_b32_e32 v41, 0xffff0000, v20
	v_cvt_pk_bf16_f32 v35, v36, v37
	v_lshl_add_u64 v[36:37], v[72:73], 0, s[28:29]
	global_store_dwordx4 v[36:37], v[32:35], off sc1
	v_lshlrev_b32_e32 v42, 16, v28
	v_and_b32_e32 v43, 0xffff0000, v28
	v_max3_f32 v34, v96, v97, v98
	v_sub_f32_e32 v32, v96, v34
	v_mul_f32_e32 v32, 0x3fb8aa3b, v32
	v_exp_f32_e32 v33, v32
	v_sub_f32_e32 v32, v97, v34
	v_mul_f32_e32 v32, 0x3fb8aa3b, v32
	v_sub_f32_e32 v34, v98, v34
	v_exp_f32_e32 v32, v32
	v_mul_f32_e32 v34, 0x3fb8aa3b, v34
	v_exp_f32_e32 v35, v34
	v_lshlrev_b32_e32 v28, 16, v29
	v_add_f32_e32 v34, v33, v32
	v_and_b32_e32 v29, 0xffff0000, v29
	v_add_f32_e32 v34, v35, v34
	v_div_scale_f32 v36, s[16:17], v34, v34, 1.0
; __device__ __forceinline__ unsigned cvt_pk_bf16(float lo, float hi) { f32x2_t v = {lo, hi}; bf16x2_t r = __builtin_convertvector(v, bf16x2_t); return __builtin_bit_cast(unsigned, r); }
; __device__ __forceinline__ float bf_lo(unsigned w) { return __uint_as_float(w << 16); }
; __device__ __forceinline__ float bf_hi(unsigned w) { return __uint_as_float(w & 0xffff0000u); }
; __global__ void __launch_bounds__(512) mega(Args a) {
;     ...
;         auto mix_item = [&](const int tok, const MixIn& m) {
;           const float mx = fmaxf(m.l0, fmaxf(m.l1, m.l2)), e0 = __expf(m.l0 - mx), e1 = __expf(m.l1 - mx), e2 = __expf(m.l2 - mx), inv = 1.f / (e0 + e1 + e2);
;           const float w0 = e0 * inv, w1 = e1 * inv, w2 = e2 * inv;
;           u32x4 w;
; #pragma unroll
;           for (int q = 0; q < 4; ++q) { const float lo = (w0 * bf_lo(m.o0[q]) + w1 * bf_lo(m.o1[q]) + w2 * bf_lo(m.o2[q])) * bf_lo(m.z[q]), hi_ = (w0 * bf_hi(m.o0[q]) + w1 * bf_hi(m.o1[q]) + w2 * bf_hi(m.o2[q])) * bf_hi(m.z[q]); w[q] = cvt_pk_bf16(lo, hi_); }
;           *(u32x4*)(Y + (size_t)tok * YW + 2048 + hg * 128 + e8) = w; };
;         int tok0 = gw;
;         for (; tok0 + 3 * NGW < MT; tok0 += 4 * NGW) {
;           const MixIn m0 = mix_load(tok0), m1 = mix_load(tok0 + NGW), m2 = mix_load(tok0 + 2 * NGW), m3 = mix_load(tok0 + 3 * NGW);
;           mix_item(tok0, m0); mix_item(tok0 + NGW, m1); mix_item(tok0 + 2 * NGW, m2); mix_item(tok0 + 3 * NGW, m3);
	v_rcp_f32_e32 v37, v36
	v_lshl_add_u64 v[72:73], v[72:73], 0, s[40:41]
	v_lshl_add_u64 v[80:81], v[80:81], 0, s[40:41]
	v_lshl_add_u64 v[82:83], v[82:83], 0, s[42:43]
	v_fma_f32 v38, -v36, v37, 1.0
	v_fmac_f32_e32 v37, v38, v37
	v_div_scale_f32 v38, vcc, 1.0, v34, 1.0
	v_mul_f32_e32 v39, v38, v37
	v_fma_f32 v40, -v36, v39, v38
	v_fmac_f32_e32 v39, v40, v37
	v_fma_f32 v36, -v36, v39, v38
	v_div_fmas_f32 v36, v36, v37, v39
	v_div_fixup_f32 v34, v36, v34, 1.0
	v_pk_mul_f32 v[32:33], v[32:33], v[34:35] op_sel_hi:[1,0]
	v_lshlrev_b32_e32 v38, 16, v16
	v_and_b32_e32 v39, 0xffff0000, v24
	v_mul_f32_e32 v36, v35, v34
	v_lshlrev_b32_e32 v34, 16, v24
	v_and_b32_e32 v35, 0xffff0000, v16
	v_pk_mul_f32 v[38:39], v[32:33], v[38:39] op_sel:[1,0] op_sel_hi:[0,1]
	v_lshlrev_b32_e32 v40, 16, v20
	v_pk_fma_f32 v[34:35], v[32:33], v[34:35], v[38:39]
	v_lshlrev_b32_e32 v24, 16, v17
	v_pk_fma_f32 v[34:35], v[36:37], v[40:41], v[34:35] op_sel_hi:[0,1,1]
	v_pk_mul_f32 v[34:35], v[34:35], v[42:43]
	v_lshlrev_b32_e32 v20, 16, v21
	v_cvt_pk_bf16_f32 v16, v34, v35
	v_lshlrev_b32_e32 v34, 16, v25
	v_and_b32_e32 v25, 0xffff0000, v25
	v_and_b32_e32 v35, 0xffff0000, v17
	v_pk_mul_f32 v[24:25], v[32:33], v[24:25] op_sel:[1,0] op_sel_hi:[0,1]
	v_and_b32_e32 v21, 0xffff0000, v21
	v_pk_fma_f32 v[24:25], v[32:33], v[34:35], v[24:25]
	v_lshlrev_b32_e32 v34, 16, v30
	v_pk_fma_f32 v[20:21], v[36:37], v[20:21], v[24:25] op_sel_hi:[0,1,1]
	v_pk_mul_f32 v[20:21], v[20:21], v[28:29]
	v_lshlrev_b32_e32 v24, 16, v18
	v_and_b32_e32 v25, 0xffff0000, v26
	v_cvt_pk_bf16_f32 v17, v20, v21
	v_lshlrev_b32_e32 v20, 16, v26
	v_and_b32_e32 v21, 0xffff0000, v18
	v_pk_mul_f32 v[24:25], v[32:33], v[24:25] op_sel:[1,0] op_sel_hi:[0,1]
	v_lshlrev_b32_e32 v28, 16, v22
	v_and_b32_e32 v29, 0xffff0000, v22
	v_pk_fma_f32 v[20:21], v[32:33], v[20:21], v[24:25]
	v_and_b32_e32 v35, 0xffff0000, v30
	v_pk_fma_f32 v[20:21], v[36:37], v[28:29], v[20:21] op_sel_hi:[0,1,1]
	v_pk_mul_f32 v[20:21], v[20:21], v[34:35]
	v_lshlrev_b32_e32 v24, 16, v19
	v_and_b32_e32 v25, 0xffff0000, v27
	v_cvt_pk_bf16_f32 v18, v20, v21
	v_lshlrev_b32_e32 v20, 16, v27
	v_and_b32_e32 v21, 0xffff0000, v19
	v_pk_mul_f32 v[24:25], v[32:33], v[24:25] op_sel:[1,0] op_sel_hi:[0,1]
	v_pk_fma_f32 v[20:21], v[32:33], v[20:21], v[24:25]
	v_lshlrev_b32_e32 v22, 16, v23
	v_and_b32_e32 v23, 0xffff0000, v23
	v_pk_fma_f32 v[20:21], v[36:37], v[22:23], v[20:21] op_sel_hi:[0,1,1]
	v_lshlrev_b32_e32 v22, 16, v31
	v_and_b32_e32 v23, 0xffff0000, v31
	v_pk_mul_f32 v[20:21], v[20:21], v[22:23]
	v_and_b32_e32 v27, 0xffff0000, v4
	v_cvt_pk_bf16_f32 v19, v20, v21
	v_mov_b64_e32 v[20:21], s[38:39]
	v_mad_i64_i32 v[22:23], s[16:17], v92, s15, v[20:21]
	v_lshl_add_u64 v[22:23], v[22:23], 0, v[192:193]
	v_lshl_add_u64 v[22:23], v[22:23], 0, v[88:89]
	v_add_co_u32_e32 v22, vcc, s33, v22
	s_waitcnt vmcnt(2)
	v_lshlrev_b32_e32 v28, 16, v12
	v_addc_co_u32_e32 v23, vcc, 0, v23, vcc
	global_store_dwordx4 v[22:23], v[16:19], off sc1
	v_and_b32_e32 v29, 0xffff0000, v12
	v_lshlrev_b32_e32 v12, 16, v13
	v_max3_f32 v18, v65, v67, v93
	v_sub_f32_e32 v16, v65, v18
	v_mul_f32_e32 v16, 0x3fb8aa3b, v16
	v_exp_f32_e32 v17, v16
	v_sub_f32_e32 v16, v67, v18
	v_mul_f32_e32 v16, 0x3fb8aa3b, v16
	v_sub_f32_e32 v18, v93, v18
	v_exp_f32_e32 v16, v16
	v_mul_f32_e32 v18, 0x3fb8aa3b, v18
	v_exp_f32_e32 v19, v18
	v_and_b32_e32 v13, 0xffff0000, v13
	v_add_f32_e32 v18, v17, v16
	v_lshl_add_u64 v[84:85], v[84:85], 0, s[44:45]
	v_add_f32_e32 v18, v19, v18
	v_div_scale_f32 v22, s[16:17], v18, v18, 1.0
	v_rcp_f32_e32 v23, v22
	v_lshl_add_u64 v[86:87], v[86:87], 0, s[46:47]
	v_fma_f32 v24, -v22, v23, 1.0
	v_fmac_f32_e32 v23, v24, v23
	v_div_scale_f32 v24, vcc, 1.0, v18, 1.0
	v_mul_f32_e32 v25, v24, v23
	v_fma_f32 v26, -v22, v25, v24
	v_fmac_f32_e32 v25, v26, v23
	v_fma_f32 v22, -v22, v25, v24
	v_div_fmas_f32 v22, v22, v23, v25
	v_div_fixup_f32 v18, v22, v18, 1.0
	v_pk_mul_f32 v[16:17], v[16:17], v[18:19] op_sel_hi:[1,0]
	v_lshlrev_b32_e32 v24, 16, v0
	v_and_b32_e32 v25, 0xffff0000, v8
	v_mul_f32_e32 v22, v19, v18
	v_lshlrev_b32_e32 v18, 16, v8
	v_and_b32_e32 v19, 0xffff0000, v0
	v_pk_mul_f32 v[24:25], v[16:17], v[24:25] op_sel:[1,0] op_sel_hi:[0,1]
	v_lshlrev_b32_e32 v26, 16, v4
	v_pk_fma_f32 v[18:19], v[16:17], v[18:19], v[24:25]
	v_lshlrev_b32_e32 v8, 16, v1
	v_pk_fma_f32 v[18:19], v[22:23], v[26:27], v[18:19] op_sel_hi:[0,1,1]
	v_pk_mul_f32 v[18:19], v[18:19], v[28:29]
	v_lshlrev_b32_e32 v4, 16, v5
	v_cvt_pk_bf16_f32 v0, v18, v19
	v_lshlrev_b32_e32 v18, 16, v9
	v_and_b32_e32 v9, 0xffff0000, v9
	v_and_b32_e32 v19, 0xffff0000, v1
	v_pk_mul_f32 v[8:9], v[16:17], v[8:9] op_sel:[1,0] op_sel_hi:[0,1]
	v_and_b32_e32 v5, 0xffff0000, v5
	v_pk_fma_f32 v[8:9], v[16:17], v[18:19], v[8:9]
	v_lshlrev_b32_e32 v18, 16, v14
	v_pk_fma_f32 v[4:5], v[22:23], v[4:5], v[8:9] op_sel_hi:[0,1,1]
	v_pk_mul_f32 v[4:5], v[4:5], v[12:13]
	v_lshlrev_b32_e32 v8, 16, v2
	v_and_b32_e32 v9, 0xffff0000, v10
	v_cvt_pk_bf16_f32 v1, v4, v5
	v_lshlrev_b32_e32 v4, 16, v10
	v_and_b32_e32 v5, 0xffff0000, v2
	v_pk_mul_f32 v[8:9], v[16:17], v[8:9] op_sel:[1,0] op_sel_hi:[0,1]
	v_lshlrev_b32_e32 v12, 16, v6
	v_and_b32_e32 v13, 0xffff0000, v6
	v_pk_fma_f32 v[4:5], v[16:17], v[4:5], v[8:9]
	v_and_b32_e32 v19, 0xffff0000, v14
	v_pk_fma_f32 v[4:5], v[22:23], v[12:13], v[4:5] op_sel_hi:[0,1,1]
	v_pk_mul_f32 v[4:5], v[4:5], v[18:19]
	v_lshlrev_b32_e32 v8, 16, v3
	v_and_b32_e32 v9, 0xffff0000, v11
	v_cvt_pk_bf16_f32 v2, v4, v5
	v_lshlrev_b32_e32 v4, 16, v11
	v_and_b32_e32 v5, 0xffff0000, v3
	v_pk_mul_f32 v[8:9], v[16:17], v[8:9] op_sel:[1,0] op_sel_hi:[0,1]
	v_pk_fma_f32 v[4:5], v[16:17], v[4:5], v[8:9]
	v_lshlrev_b32_e32 v6, 16, v7
	v_and_b32_e32 v7, 0xffff0000, v7
	v_pk_fma_f32 v[4:5], v[22:23], v[6:7], v[4:5] op_sel_hi:[0,1,1]
	v_lshlrev_b32_e32 v6, 16, v15
	v_and_b32_e32 v7, 0xffff0000, v15
	v_pk_mul_f32 v[4:5], v[4:5], v[6:7]
	s_nop 0
	v_cvt_pk_bf16_f32 v3, v4, v5
	v_mad_i64_i32 v[4:5], s[16:17], v90, s15, v[20:21]
	v_lshl_add_u64 v[4:5], v[4:5], 0, v[192:193]
	v_lshl_add_u64 v[4:5], v[4:5], 0, v[88:89]
	v_add_co_u32_e32 v4, vcc, s33, v4
	s_nop 1
	v_addc_co_u32_e32 v5, vcc, 0, v5, vcc
	global_store_dwordx4 v[4:5], v[0:3], off sc1
	s_nop 1
	v_add_u32_e32 v0, s2, v64
	v_cmp_lt_i32_e32 vcc, s20, v0
	s_or_b64 s[48:49], vcc, s[48:49]
	s_andn2_b64 exec, exec, s[48:49]
	s_cbranch_execnz .LBB0_190
	s_movk_i32 s69, 0x1400
	s_or_b64 exec, exec, s[48:49]

; __device__ __forceinline__ unsigned cvt_pk_bf16(float lo, float hi) { f32x2_t v = {lo, hi}; bf16x2_t r = __builtin_convertvector(v, bf16x2_t); return __builtin_bit_cast(unsigned, r); }
; __device__ __forceinline__ float bf_lo(unsigned w) { return __uint_as_float(w << 16); }
; __device__ __forceinline__ float bf_hi(unsigned w) { return __uint_as_float(w & 0xffff0000u); }
; __global__ void __launch_bounds__(512) mega(Args a) {
;     ...
;         auto mix_load = [&](const int tok) { MixIn m;
;           m.l0 = LSE[((size_t)0 * MT + tok) * 4 + hg]; m.l1 = LSE[((size_t)1 * MT + tok) * 4 + hg]; m.l2 = LSE[((size_t)2 * MT + tok) * 4 + hg];
;           m.o0 = __builtin_nontemporal_load((const u32x4*)(OC + ((size_t)0 * MT + tok) * 512 + hg * 128 + e8)); m.o1 = __builtin_nontemporal_load((const u32x4*)(OC + ((size_t)1 * MT + tok) * 512 + hg * 128 + e8));
;           m.o2 = __builtin_nontemporal_load((const u32x4*)(OC + ((size_t)2 * MT + tok) * 512 + hg * 128 + e8)); m.z = *(const u32x4*)(PROJ + (size_t)tok * NIN + C_ZC + hg * 128 + e8); return m; };
;         auto mix_item = [&](const int tok, const MixIn& m) {
;           const float mx = fmaxf(m.l0, fmaxf(m.l1, m.l2)), e0 = __expf(m.l0 - mx), e1 = __expf(m.l1 - mx), e2 = __expf(m.l2 - mx), inv = 1.f / (e0 + e1 + e2);
;           const float w0 = e0 * inv, w1 = e1 * inv, w2 = e2 * inv;
;           u32x4 w;
; #pragma unroll
;           for (int q = 0; q < 4; ++q) { const float lo = (w0 * bf_lo(m.o0[q]) + w1 * bf_lo(m.o1[q]) + w2 * bf_lo(m.o2[q])) * bf_lo(m.z[q]), hi_ = (w0 * bf_hi(m.o0[q]) + w1 * bf_hi(m.o1[q]) + w2 * bf_hi(m.o2[q])) * bf_hi(m.z[q]); w[q] = cvt_pk_bf16(lo, hi_); }
;           *(u32x4*)(Y + (size_t)tok * YW + 2048 + hg * 128 + e8) = w; };
;     ...
;         for (; tok0 < MT; tok0 += NGW) mix_item(tok0, mix_load(tok0));
.LBB0_194:
	v_lshl_add_u64 v[0:1], v[10:11], 0, s[28:29]
	v_add_co_u32_e32 v2, vcc, 0x48000000, v0
	v_lshl_add_u64 v[16:17], v[8:9], 0, s[28:29]
	s_nop 0
	v_addc_co_u32_e32 v3, vcc, 0, v1, vcc
	global_load_dword v24, v[2:3], off
	v_add_co_u32_e32 v2, vcc, 0x48040000, v0
	s_waitcnt vmcnt(0)
	v_lshl_add_u64 v[20:21], v[6:7], 0, s[28:29]
	v_addc_co_u32_e32 v3, vcc, 0, v1, vcc
	v_add_co_u32_e32 v0, vcc, 0x48080000, v0
	global_load_dword v26, v[2:3], off
	s_nop 0
	v_addc_co_u32_e32 v1, vcc, 0, v1, vcc
	global_load_dword v27, v[0:1], off
	v_add_co_u32_e32 v0, vcc, 0x45000000, v16
	global_load_dwordx4 v[20:23], v[20:21], off
	s_nop 0
	v_addc_co_u32_e32 v1, vcc, 0, v17, vcc
	v_add_co_u32_e32 v12, vcc, 0x46000000, v16
	global_load_dwordx4 v[0:3], v[0:1], off nt
	s_nop 0
	v_addc_co_u32_e32 v13, vcc, 0, v17, vcc
	global_load_dwordx4 v[12:15], v[12:13], off nt
	v_add_co_u32_e32 v16, vcc, 0x47000000, v16
	v_add_u32_e32 v64, s10, v64
	s_nop 0
	v_addc_co_u32_e32 v17, vcc, 0, v17, vcc
	global_load_dwordx4 v[16:19], v[16:17], off nt
	v_lshl_add_u64 v[6:7], v[6:7], 0, s[36:37]
	v_lshl_add_u64 v[8:9], v[8:9], 0, s[40:41]
	v_lshl_add_u64 v[10:11], v[10:11], 0, s[42:43]
	s_waitcnt vmcnt(4)
	v_max3_f32 v28, v24, v26, v27
	v_sub_f32_e32 v24, v24, v28
	v_mul_f32_e32 v24, 0x3fb8aa3b, v24
	v_exp_f32_e32 v25, v24
	v_sub_f32_e32 v24, v26, v28
	v_mul_f32_e32 v24, 0x3fb8aa3b, v24
	v_sub_f32_e32 v26, v27, v28
	v_exp_f32_e32 v24, v24
	v_mul_f32_e32 v26, 0x3fb8aa3b, v26
	v_exp_f32_e32 v27, v26
	s_waitcnt vmcnt(3)
	v_lshlrev_b32_e32 v34, 16, v20
	v_add_f32_e32 v26, v25, v24
	v_and_b32_e32 v35, 0xffff0000, v20
	v_add_f32_e32 v26, v27, v26
	v_div_scale_f32 v28, s[16:17], v26, v26, 1.0
	v_rcp_f32_e32 v29, v28
	s_waitcnt vmcnt(0)
	v_and_b32_e32 v33, 0xffff0000, v16
	v_lshlrev_b32_e32 v20, 16, v21
	v_and_b32_e32 v21, 0xffff0000, v21
	v_fma_f32 v30, -v28, v29, 1.0
	v_fmac_f32_e32 v29, v30, v29
	v_div_scale_f32 v30, vcc, 1.0, v26, 1.0
	v_mul_f32_e32 v31, v30, v29
	v_fma_f32 v32, -v28, v31, v30
	v_fmac_f32_e32 v31, v32, v29
	v_fma_f32 v28, -v28, v31, v30
	v_div_fmas_f32 v28, v28, v29, v31
	v_div_fixup_f32 v26, v28, v26, 1.0
	v_pk_mul_f32 v[24:25], v[24:25], v[26:27] op_sel_hi:[1,0]
	v_lshlrev_b32_e32 v30, 16, v0
	v_and_b32_e32 v31, 0xffff0000, v12
	v_mul_f32_e32 v28, v27, v26
	v_lshlrev_b32_e32 v26, 16, v12
	v_and_b32_e32 v27, 0xffff0000, v0
	v_pk_mul_f32 v[30:31], v[24:25], v[30:31] op_sel:[1,0] op_sel_hi:[0,1]
	v_lshlrev_b32_e32 v32, 16, v16
	v_pk_fma_f32 v[26:27], v[24:25], v[26:27], v[30:31]
	v_lshlrev_b32_e32 v12, 16, v1
	v_pk_fma_f32 v[26:27], v[28:29], v[32:33], v[26:27] op_sel_hi:[0,1,1]
	v_pk_mul_f32 v[26:27], v[26:27], v[34:35]
	v_lshlrev_b32_e32 v16, 16, v17
	v_cvt_pk_bf16_f32 v0, v26, v27
	v_lshlrev_b32_e32 v26, 16, v13
	v_and_b32_e32 v13, 0xffff0000, v13
	v_and_b32_e32 v27, 0xffff0000, v1
	v_pk_mul_f32 v[12:13], v[24:25], v[12:13] op_sel:[1,0] op_sel_hi:[0,1]
	v_and_b32_e32 v17, 0xffff0000, v17
	v_pk_fma_f32 v[12:13], v[24:25], v[26:27], v[12:13]
	v_lshlrev_b32_e32 v26, 16, v22
	v_pk_fma_f32 v[12:13], v[28:29], v[16:17], v[12:13] op_sel_hi:[0,1,1]
	v_pk_mul_f32 v[12:13], v[12:13], v[20:21]
	v_lshlrev_b32_e32 v16, 16, v2
	v_and_b32_e32 v17, 0xffff0000, v14
	v_cvt_pk_bf16_f32 v1, v12, v13
	v_lshlrev_b32_e32 v12, 16, v14
	v_and_b32_e32 v13, 0xffff0000, v2
	v_pk_mul_f32 v[16:17], v[24:25], v[16:17] op_sel:[1,0] op_sel_hi:[0,1]
	v_lshlrev_b32_e32 v20, 16, v18
	v_and_b32_e32 v21, 0xffff0000, v18
	v_pk_fma_f32 v[12:13], v[24:25], v[12:13], v[16:17]
	v_and_b32_e32 v27, 0xffff0000, v22
	v_pk_fma_f32 v[12:13], v[28:29], v[20:21], v[12:13] op_sel_hi:[0,1,1]
	v_pk_mul_f32 v[12:13], v[12:13], v[26:27]
	v_lshlrev_b32_e32 v14, 16, v3
	v_cvt_pk_bf16_f32 v2, v12, v13
	v_lshlrev_b32_e32 v12, 16, v15
	v_and_b32_e32 v15, 0xffff0000, v15
	v_and_b32_e32 v13, 0xffff0000, v3
	v_pk_mul_f32 v[14:15], v[24:25], v[14:15] op_sel:[1,0] op_sel_hi:[0,1]
	v_pk_fma_f32 v[12:13], v[24:25], v[12:13], v[14:15]
	v_lshlrev_b32_e32 v14, 16, v19
	v_and_b32_e32 v15, 0xffff0000, v19
	v_pk_fma_f32 v[12:13], v[28:29], v[14:15], v[12:13] op_sel_hi:[0,1,1]
	v_lshlrev_b32_e32 v14, 16, v23
	v_and_b32_e32 v15, 0xffff0000, v23
	v_pk_mul_f32 v[12:13], v[12:13], v[14:15]
	v_cmp_lt_i32_e32 vcc, s15, v64
	v_cvt_pk_bf16_f32 v3, v12, v13
	v_lshl_add_u64 v[12:13], v[4:5], 0, s[28:29]
	v_lshl_add_u64 v[4:5], v[4:5], 0, s[30:31]
	s_or_b64 s[44:45], vcc, s[44:45]
	global_store_dwordx4 v[12:13], v[0:3], off sc1
	s_andn2_b64 exec, exec, s[44:45]
	s_cbranch_execnz .LBB0_194

; __device__ __forceinline__ unsigned cvt_pk_bf16(float lo, float hi) { f32x2_t v = {lo, hi}; bf16x2_t r = __builtin_convertvector(v, bf16x2_t); return __builtin_bit_cast(unsigned, r); }
; __device__ __forceinline__ float bf_lo(unsigned w) { return __uint_as_float(w << 16); }
; __device__ __forceinline__ float bf_hi(unsigned w) { return __uint_as_float(w & 0xffff0000u); }
; __global__ void __launch_bounds__(512) mega(Args a) {
;     ...
;           const int tok = it / 3, quad = it % 3, hh = quad * 4 + sb, b = tok >> 13, s = tok & (SEQ - 1);
;           float xv[8];
; #pragma unroll
;           for (int q = 0; q < 4; ++q) { xv[2 * q] = bf_lo(raw[q]); xv[2 * q + 1] = bf_hi(raw[q]); }
;           u32x4 ov = raw;
;           if (hh < 10) {
;             float ss = 0.f;
; #pragma unroll
;             for (int j = 0; j < 8; ++j) ss += xv[j] * xv[j];
;             ss += __shfl_xor(ss, 1); ss += __shfl_xor(ss, 2); ss += __shfl_xor(ss, 4); ss += __shfl_xor(ss, 8);
;             const float rn = rsqrtf(ss * (1.f / 128.f) + EPS);
;             const float* gp = (hh < 8 ? qn_g : kn_g) + l * 128 + u * 8;
;             const float pos = (float)((u < 8) ? (s >> 6) : (s & 63));
;             const bool upper = (u & 4) != 0;
;             float yv[8];
; #pragma unroll
;             for (int j = 0; j < 8; ++j) {
;               const float y = xv[j] * rn * gp[j];
;               const float p = __shfl_xor(y, 4);
;               const int fi = (u & 3) * 8 + j;
;               const float rev = pos * __builtin_amdgcn_exp2f(-0.41524101186092029f * (float)fi) * 0.15915494309189535f;
;               const float cs = __builtin_amdgcn_cosf(rev), sn = __builtin_amdgcn_sinf(rev);
;               yv[j] = upper ? (p * sn + y * cs) : (y * cs - p * sn);
;             }
; #pragma unroll
;             for (int q = 0; q < 4; ++q) ov[q] = cvt_pk_bf16(yv[2 * q], yv[2 * q + 1]);
;           }
;           bf16_t* dst = hh < 8 ? QBc + ((size_t)(b * 8 + hh) * SEQ + s) * 128 : (hh < 10 ? KBc + ((size_t)(b * 2 + hh - 8) * SEQ + s) * 128 : VBc + ((size_t)(b * 2 + hh - 10) * SEQ + s) * 128);
;           *(u32x4*)(dst + u * 8) = ov;
.LBB0_231:
	s_andn2_saveexec_b64 s[0:1], s[0:1]
	v_lshl_add_u32 v24, v25, 3, v23
	v_mov_b64_e32 v[26:27], s[40:41]
	s_or_b64 exec, exec, s[0:1]
	v_ashrrev_i32_e32 v25, 31, v24
	v_lshlrev_b64 v[24:25], 21, v[24:25]
	v_lshl_add_u64 v[24:25], v[26:27], 0, v[24:25]
	v_lshlrev_b32_e32 v26, 8, v50
	v_mov_b32_e32 v27, v193
	v_lshl_add_u64 v[24:25], v[24:25], 0, v[26:27]
	v_lshl_add_u64 v[24:25], v[24:25], 0, v[192:193]
	s_waitcnt vmcnt(3)
	global_store_dwordx4 v[24:25], v[12:15], off sc1
	s_nop 1
	v_lshl_or_b32 v13, v48, 2, v19
	v_cmp_lt_i32_e32 vcc, 9, v13
	s_and_saveexec_b64 s[0:1], vcc
	s_xor_b64 s[0:1], exec, s[0:1]
	s_or_saveexec_b64 s[2:3], s[0:1]
	v_and_b32_e32 v24, 0x1fff, v47
	s_xor_b64 exec, exec, s[2:3]
	s_cbranch_execz .LBB0_235
	v_mov_b32_e32 v12, s91
	v_mov_b32_e32 v14, s89
	v_cmp_gt_i32_e64 s[0:1], 8, v13
	v_mov_b32_e32 v23, v193
	s_waitcnt vmcnt(3)
	v_lshlrev_b32_e32 v26, 16, v11
	v_cndmask_b32_e64 v15, v12, v14, s[0:1]
	v_mov_b32_e32 v12, s90
	v_mov_b32_e32 v14, s88
	v_cndmask_b32_e64 v14, v12, v14, s[0:1]
	v_lshl_add_u64 v[14:15], s[8:9], 2, v[14:15]
	v_lshl_add_u64 v[14:15], v[14:15], 0, v[22:23]
	global_load_dwordx4 v[48:51], v[14:15], off
	global_load_dwordx4 v[52:55], v[14:15], off offset:16
	v_lshlrev_b32_e32 v14, 16, v8
	v_and_b32_e32 v15, 0xffff0000, v8
	v_lshrrev_b32_e32 v12, 6, v24
	v_and_b32_e32 v23, 63, v47
	v_and_b32_e32 v27, 0xffff0000, v11
	v_lshlrev_b32_e32 v56, 16, v10
	v_and_b32_e32 v57, 0xffff0000, v10
	v_lshlrev_b32_e32 v10, 16, v9
	v_and_b32_e32 v11, 0xffff0000, v9
	v_pk_mul_f32 v[62:63], v[14:15], v[14:15]
	v_cndmask_b32_e64 v12, v23, v12, s[36:37]
	v_pk_mul_f32 v[60:61], v[10:11], v[10:11]
	v_add_f32_e32 v23, v62, v63
	v_add_f32_e32 v23, v60, v23
	v_pk_mul_f32 v[58:59], v[56:57], v[56:57]
	v_add_f32_e32 v23, v61, v23
	v_add_f32_e32 v23, v58, v23
	v_pk_mul_f32 v[8:9], v[26:27], v[26:27]
	v_add_f32_e32 v23, v59, v23
	v_add_f32_e32 v8, v8, v23
	v_add_f32_e32 v9, v9, v8
	ds_bpermute_b32 v23, v31, v9
	v_cvt_f32_ubyte0_e32 v12, v12
	v_mul_f32_e32 v25, v35, v12
	v_mul_f32_e32 v25, 0.15915494, v25
	v_cos_f32_e32 v8, v25
	s_waitcnt lgkmcnt(0)
	v_add_f32_e32 v23, v9, v23
	ds_bpermute_b32 v61, v32, v23
	v_sin_f32_e32 v58, v25
	s_mov_b32 s0, 0x800000
	v_mul_f32_e32 v62, v36, v12
	v_mul_f32_e32 v63, v37, v12
	s_waitcnt lgkmcnt(0)
	v_add_f32_e32 v23, v23, v61
	ds_bpermute_b32 v25, v33, v23
	v_mul_f32_e32 v64, v38, v12
	v_mul_f32_e32 v65, v39, v12
	v_mul_f32_e32 v66, v40, v12
	v_mul_f32_e32 v67, v41, v12
	s_waitcnt lgkmcnt(0)
	v_add_f32_e32 v23, v23, v25
	ds_bpermute_b32 v25, v34, v23
	v_mul_f32_e32 v12, v42, v12
	v_mul_f32_e32 v65, 0.15915494, v65
	v_mul_f32_e32 v68, 0.15915494, v66
	v_mul_f32_e32 v69, 0.15915494, v67
	s_waitcnt lgkmcnt(0)
	v_add_f32_e32 v23, v23, v25
	v_fmamk_f32 v23, v23, 0x3c000000, v227
	v_mul_f32_e32 v25, 0x4b800000, v23
	v_cmp_gt_f32_e64 s[0:1], s0, v23
	v_mul_f32_e32 v12, 0.15915494, v12
	v_mul_f32_e32 v60, 0.15915494, v62
	v_cndmask_b32_e64 v23, v23, v25, s[0:1]
	v_rsq_f32_e32 v23, v23
	v_mul_f32_e32 v62, 0.15915494, v63
	v_mul_f32_e32 v63, 0.15915494, v64
	v_cos_f32_e32 v64, v65
	v_sin_f32_e32 v66, v65
	v_cos_f32_e32 v65, v68
	v_sin_f32_e32 v67, v68
	v_cos_f32_e32 v68, v69
	v_sin_f32_e32 v70, v69
	v_cos_f32_e32 v69, v12
	v_sin_f32_e32 v71, v12
	v_mul_f32_e32 v12, 0x45800000, v23
	v_cndmask_b32_e64 v12, v23, v12, s[0:1]
	v_pk_mul_f32 v[14:15], v[12:13], v[14:15] op_sel_hi:[0,1]
	v_pk_mul_f32 v[10:11], v[12:13], v[10:11] op_sel_hi:[0,1]
	v_sin_f32_e32 v59, v60
	v_cos_f32_e32 v9, v60
	v_cos_f32_e32 v60, v62
	v_sin_f32_e32 v62, v62
	v_cos_f32_e32 v61, v63
	v_sin_f32_e32 v63, v63
	v_pk_mul_f32 v[26:27], v[12:13], v[26:27] op_sel_hi:[0,1]
	s_waitcnt vmcnt(1)
	v_pk_mul_f32 v[14:15], v[48:49], v[14:15]
	ds_bpermute_b32 v48, v33, v14
	ds_bpermute_b32 v49, v33, v15
	v_pk_mul_f32 v[10:11], v[50:51], v[10:11]
	ds_bpermute_b32 v50, v33, v10
	ds_bpermute_b32 v51, v33, v11
	s_waitcnt vmcnt(0)
	v_pk_mul_f32 v[26:27], v[26:27], v[54:55]
	s_waitcnt lgkmcnt(2)
	v_pk_mul_f32 v[48:49], v[58:59], v[48:49]
	s_nop 0
	v_cndmask_b32_e64 v49, v49, -v49, s[38:39]
	v_cndmask_b32_e64 v48, v48, -v48, s[38:39]
	v_pk_fma_f32 v[8:9], v[8:9], v[14:15], v[48:49]
	s_waitcnt lgkmcnt(0)
	v_pk_mul_f32 v[14:15], v[62:63], v[50:51]
	ds_bpermute_b32 v50, v33, v26
	v_cndmask_b32_e64 v15, v15, -v15, s[38:39]
	v_cndmask_b32_e64 v14, v14, -v14, s[38:39]
	v_pk_fma_f32 v[10:11], v[60:61], v[10:11], v[14:15]
	v_pk_mul_f32 v[14:15], v[12:13], v[56:57] op_sel_hi:[0,1]
	v_pk_mul_f32 v[14:15], v[14:15], v[52:53]
	ds_bpermute_b32 v48, v33, v14
	ds_bpermute_b32 v49, v33, v15
	ds_bpermute_b32 v51, v33, v27
	v_cvt_pk_bf16_f32 v8, v8, v9
	v_cvt_pk_bf16_f32 v9, v10, v11
	s_waitcnt lgkmcnt(1)
	v_pk_mul_f32 v[48:49], v[66:67], v[48:49]
	s_nop 0
	v_cndmask_b32_e64 v49, v49, -v49, s[38:39]
	v_cndmask_b32_e64 v48, v48, -v48, s[38:39]
	v_pk_fma_f32 v[14:15], v[64:65], v[14:15], v[48:49]
	s_waitcnt lgkmcnt(0)
	v_pk_mul_f32 v[48:49], v[70:71], v[50:51]
	v_cvt_pk_bf16_f32 v10, v14, v15
	v_cndmask_b32_e64 v49, v49, -v49, s[38:39]
	v_cndmask_b32_e64 v48, v48, -v48, s[38:39]
	v_pk_fma_f32 v[26:27], v[68:69], v[26:27], v[48:49]
	s_nop 0
	v_cvt_pk_bf16_f32 v11, v26, v27

; __device__ __forceinline__ unsigned cvt_pk_bf16(float lo, float hi) { f32x2_t v = {lo, hi}; bf16x2_t r = __builtin_convertvector(v, bf16x2_t); return __builtin_bit_cast(unsigned, r); }
; __device__ __forceinline__ float bf_lo(unsigned w) { return __uint_as_float(w << 16); }
; __device__ __forceinline__ float bf_hi(unsigned w) { return __uint_as_float(w & 0xffff0000u); }
; __global__ void __launch_bounds__(512) mega(Args a) {
;     ...
;           const int tok = it / 3, quad = it % 3, hh = quad * 4 + sb, b = tok >> 13, s = tok & (SEQ - 1);
;           float xv[8];
; #pragma unroll
;           for (int q = 0; q < 4; ++q) { xv[2 * q] = bf_lo(raw[q]); xv[2 * q + 1] = bf_hi(raw[q]); }
;           u32x4 ov = raw;
;           if (hh < 10) {
;             float ss = 0.f;
; #pragma unroll
;             for (int j = 0; j < 8; ++j) ss += xv[j] * xv[j];
;             ss += __shfl_xor(ss, 1); ss += __shfl_xor(ss, 2); ss += __shfl_xor(ss, 4); ss += __shfl_xor(ss, 8);
;             const float rn = rsqrtf(ss * (1.f / 128.f) + EPS);
;             const float* gp = (hh < 8 ? qn_g : kn_g) + l * 128 + u * 8;
;             const float pos = (float)((u < 8) ? (s >> 6) : (s & 63));
;             const bool upper = (u & 4) != 0;
;             float yv[8];
; #pragma unroll
;             for (int j = 0; j < 8; ++j) {
;               const float y = xv[j] * rn * gp[j];
;               const float p = __shfl_xor(y, 4);
;               const int fi = (u & 3) * 8 + j;
;               const float rev = pos * __builtin_amdgcn_exp2f(-0.41524101186092029f * (float)fi) * 0.15915494309189535f;
;               const float cs = __builtin_amdgcn_cosf(rev), sn = __builtin_amdgcn_sinf(rev);
;               yv[j] = upper ? (p * sn + y * cs) : (y * cs - p * sn);
;             }
; #pragma unroll
;             for (int q = 0; q < 4; ++q) ov[q] = cvt_pk_bf16(yv[2 * q], yv[2 * q + 1]);
;           }
;           bf16_t* dst = hh < 8 ? QBc + ((size_t)(b * 8 + hh) * SEQ + s) * 128 : (hh < 10 ? KBc + ((size_t)(b * 2 + hh - 8) * SEQ + s) * 128 : VBc + ((size_t)(b * 2 + hh - 10) * SEQ + s) * 128);
;           *(u32x4*)(dst + u * 8) = ov;
.LBB0_241:
	s_andn2_saveexec_b64 s[0:1], s[0:1]
	v_lshl_add_u32 v12, v23, 3, v13
	v_mov_b64_e32 v[14:15], s[40:41]
	s_or_b64 exec, exec, s[0:1]
	v_ashrrev_i32_e32 v13, 31, v12
	v_lshlrev_b64 v[12:13], 21, v[12:13]
	v_lshl_add_u64 v[12:13], v[14:15], 0, v[12:13]
	v_lshlrev_b32_e32 v14, 8, v24
	v_mov_b32_e32 v15, v193
	v_lshl_add_u64 v[12:13], v[12:13], 0, v[14:15]
	v_lshl_add_u64 v[12:13], v[12:13], 0, v[192:193]
	s_waitcnt vmcnt(3)
	global_store_dwordx4 v[12:13], v[8:11], off sc1
	s_nop 1
	v_lshl_or_b32 v9, v46, 2, v19
	v_cmp_lt_i32_e32 vcc, 9, v9
	s_and_saveexec_b64 s[0:1], vcc
	s_xor_b64 s[0:1], exec, s[0:1]
	s_or_saveexec_b64 s[2:3], s[0:1]
	v_and_b32_e32 v12, 0x1fff, v45
	s_xor_b64 exec, exec, s[2:3]
	s_cbranch_execz .LBB0_245
	v_mov_b32_e32 v8, s91
	v_mov_b32_e32 v10, s89
	v_cmp_gt_i32_e64 s[0:1], 8, v9
	v_mov_b32_e32 v23, v193
	v_and_b32_e32 v13, 63, v45
	v_cndmask_b32_e64 v11, v8, v10, s[0:1]
	v_mov_b32_e32 v8, s90
	v_mov_b32_e32 v10, s88
	v_cndmask_b32_e64 v10, v8, v10, s[0:1]
	v_lshl_add_u64 v[10:11], s[8:9], 2, v[10:11]
	v_lshl_add_u64 v[10:11], v[10:11], 0, v[22:23]
	global_load_dwordx4 v[24:27], v[10:11], off
	global_load_dwordx4 v[46:49], v[10:11], off offset:16
	s_waitcnt vmcnt(5)
	v_lshlrev_b32_e32 v10, 16, v4
	v_and_b32_e32 v11, 0xffff0000, v4
	v_lshrrev_b32_e32 v8, 6, v12
	v_lshlrev_b32_e32 v14, 16, v7
	v_and_b32_e32 v15, 0xffff0000, v7
	v_lshlrev_b32_e32 v50, 16, v6
	v_and_b32_e32 v51, 0xffff0000, v6
	v_lshlrev_b32_e32 v6, 16, v5
	v_and_b32_e32 v7, 0xffff0000, v5
	v_pk_mul_f32 v[56:57], v[10:11], v[10:11]
	v_cndmask_b32_e64 v8, v13, v8, s[36:37]
	v_pk_mul_f32 v[54:55], v[6:7], v[6:7]
	v_add_f32_e32 v13, v56, v57
	v_add_f32_e32 v13, v54, v13
	v_pk_mul_f32 v[52:53], v[50:51], v[50:51]
	v_add_f32_e32 v13, v55, v13
	v_add_f32_e32 v13, v52, v13
	v_pk_mul_f32 v[4:5], v[14:15], v[14:15]
	v_add_f32_e32 v13, v53, v13
	v_add_f32_e32 v4, v4, v13
	v_add_f32_e32 v5, v5, v4
	ds_bpermute_b32 v13, v31, v5
	v_cvt_f32_ubyte0_e32 v8, v8
	v_mul_f32_e32 v23, v35, v8
	v_mul_f32_e32 v23, 0.15915494, v23
	v_cos_f32_e32 v4, v23
	s_waitcnt lgkmcnt(0)
	v_add_f32_e32 v13, v5, v13
	ds_bpermute_b32 v55, v32, v13
	v_sin_f32_e32 v52, v23
	s_mov_b32 s0, 0x800000
	v_mul_f32_e32 v56, v36, v8
	v_mul_f32_e32 v57, v37, v8
	s_waitcnt lgkmcnt(0)
	v_add_f32_e32 v13, v13, v55
	ds_bpermute_b32 v23, v33, v13
	v_mul_f32_e32 v58, v38, v8
	v_mul_f32_e32 v59, v39, v8
	v_mul_f32_e32 v60, v40, v8
	v_mul_f32_e32 v61, v41, v8
	s_waitcnt lgkmcnt(0)
	v_add_f32_e32 v13, v13, v23
	ds_bpermute_b32 v23, v34, v13
	v_mul_f32_e32 v8, v42, v8
	v_mul_f32_e32 v59, 0.15915494, v59
	v_mul_f32_e32 v62, 0.15915494, v60
	v_mul_f32_e32 v63, 0.15915494, v61
	s_waitcnt lgkmcnt(0)
	v_add_f32_e32 v13, v13, v23
	v_fmamk_f32 v13, v13, 0x3c000000, v227
	v_mul_f32_e32 v23, 0x4b800000, v13
	v_cmp_gt_f32_e64 s[0:1], s0, v13
	v_mul_f32_e32 v8, 0.15915494, v8
	v_mul_f32_e32 v54, 0.15915494, v56
	v_cndmask_b32_e64 v13, v13, v23, s[0:1]
	v_rsq_f32_e32 v13, v13
	v_mul_f32_e32 v56, 0.15915494, v57
	v_mul_f32_e32 v57, 0.15915494, v58
	v_cos_f32_e32 v58, v59
	v_sin_f32_e32 v60, v59
	v_cos_f32_e32 v59, v62
	v_sin_f32_e32 v61, v62
	v_cos_f32_e32 v62, v63
	v_sin_f32_e32 v64, v63
	v_cos_f32_e32 v63, v8
	v_sin_f32_e32 v65, v8
	v_mul_f32_e32 v8, 0x45800000, v13
	v_cndmask_b32_e64 v8, v13, v8, s[0:1]
	v_pk_mul_f32 v[10:11], v[8:9], v[10:11] op_sel_hi:[0,1]
	v_pk_mul_f32 v[6:7], v[8:9], v[6:7] op_sel_hi:[0,1]
	v_sin_f32_e32 v53, v54
	v_cos_f32_e32 v5, v54
	v_cos_f32_e32 v54, v56
	v_sin_f32_e32 v56, v56
	v_cos_f32_e32 v55, v57
	v_sin_f32_e32 v57, v57
	v_pk_mul_f32 v[14:15], v[8:9], v[14:15] op_sel_hi:[0,1]
	s_waitcnt vmcnt(1)
	v_pk_mul_f32 v[10:11], v[24:25], v[10:11]
	ds_bpermute_b32 v24, v33, v10
	ds_bpermute_b32 v25, v33, v11
	v_pk_mul_f32 v[6:7], v[26:27], v[6:7]
	ds_bpermute_b32 v26, v33, v6
	ds_bpermute_b32 v27, v33, v7
	s_waitcnt vmcnt(0)
	v_pk_mul_f32 v[14:15], v[14:15], v[48:49]
	s_waitcnt lgkmcnt(2)
	v_pk_mul_f32 v[24:25], v[52:53], v[24:25]
	s_nop 0
	v_cndmask_b32_e64 v25, v25, -v25, s[38:39]
	v_cndmask_b32_e64 v24, v24, -v24, s[38:39]
	v_pk_fma_f32 v[4:5], v[4:5], v[10:11], v[24:25]
	s_waitcnt lgkmcnt(0)
	v_pk_mul_f32 v[10:11], v[56:57], v[26:27]
	ds_bpermute_b32 v26, v33, v14
	v_cndmask_b32_e64 v11, v11, -v11, s[38:39]
	v_cndmask_b32_e64 v10, v10, -v10, s[38:39]
	v_pk_fma_f32 v[6:7], v[54:55], v[6:7], v[10:11]
	v_pk_mul_f32 v[10:11], v[8:9], v[50:51] op_sel_hi:[0,1]
	v_pk_mul_f32 v[10:11], v[10:11], v[46:47]
	ds_bpermute_b32 v24, v33, v10
	ds_bpermute_b32 v25, v33, v11
	ds_bpermute_b32 v27, v33, v15
	v_cvt_pk_bf16_f32 v4, v4, v5
	v_cvt_pk_bf16_f32 v5, v6, v7
	s_waitcnt lgkmcnt(1)
	v_pk_mul_f32 v[24:25], v[60:61], v[24:25]
	s_nop 0
	v_cndmask_b32_e64 v25, v25, -v25, s[38:39]
	v_cndmask_b32_e64 v24, v24, -v24, s[38:39]
	v_pk_fma_f32 v[10:11], v[58:59], v[10:11], v[24:25]
	s_waitcnt lgkmcnt(0)
	v_pk_mul_f32 v[24:25], v[64:65], v[26:27]
	v_cvt_pk_bf16_f32 v6, v10, v11
	v_cndmask_b32_e64 v25, v25, -v25, s[38:39]
	v_cndmask_b32_e64 v24, v24, -v24, s[38:39]
	v_pk_fma_f32 v[14:15], v[62:63], v[14:15], v[24:25]
	s_nop 0
	v_cvt_pk_bf16_f32 v7, v14, v15

; __device__ __forceinline__ unsigned cvt_pk_bf16(float lo, float hi) { f32x2_t v = {lo, hi}; bf16x2_t r = __builtin_convertvector(v, bf16x2_t); return __builtin_bit_cast(unsigned, r); }
; __device__ __forceinline__ float bf_lo(unsigned w) { return __uint_as_float(w << 16); }
; __device__ __forceinline__ float bf_hi(unsigned w) { return __uint_as_float(w & 0xffff0000u); }
; __global__ void __launch_bounds__(512) mega(Args a) {
;     ...
;           const int tok = it / 3, quad = it % 3, hh = quad * 4 + sb, b = tok >> 13, s = tok & (SEQ - 1);
;           float xv[8];
; #pragma unroll
;           for (int q = 0; q < 4; ++q) { xv[2 * q] = bf_lo(raw[q]); xv[2 * q + 1] = bf_hi(raw[q]); }
;           u32x4 ov = raw;
;           if (hh < 10) {
;             float ss = 0.f;
; #pragma unroll
;             for (int j = 0; j < 8; ++j) ss += xv[j] * xv[j];
;             ss += __shfl_xor(ss, 1); ss += __shfl_xor(ss, 2); ss += __shfl_xor(ss, 4); ss += __shfl_xor(ss, 8);
;             const float rn = rsqrtf(ss * (1.f / 128.f) + EPS);
;             const float* gp = (hh < 8 ? qn_g : kn_g) + l * 128 + u * 8;
;             const float pos = (float)((u < 8) ? (s >> 6) : (s & 63));
;             const bool upper = (u & 4) != 0;
;             float yv[8];
; #pragma unroll
;             for (int j = 0; j < 8; ++j) {
;               const float y = xv[j] * rn * gp[j];
;               const float p = __shfl_xor(y, 4);
;               const int fi = (u & 3) * 8 + j;
;               const float rev = pos * __builtin_amdgcn_exp2f(-0.41524101186092029f * (float)fi) * 0.15915494309189535f;
;               const float cs = __builtin_amdgcn_cosf(rev), sn = __builtin_amdgcn_sinf(rev);
;               yv[j] = upper ? (p * sn + y * cs) : (y * cs - p * sn);
;             }
; #pragma unroll
;             for (int q = 0; q < 4; ++q) ov[q] = cvt_pk_bf16(yv[2 * q], yv[2 * q + 1]);
;           }
;           bf16_t* dst = hh < 8 ? QBc + ((size_t)(b * 8 + hh) * SEQ + s) * 128 : (hh < 10 ? KBc + ((size_t)(b * 2 + hh - 8) * SEQ + s) * 128 : VBc + ((size_t)(b * 2 + hh - 10) * SEQ + s) * 128);
;           *(u32x4*)(dst + u * 8) = ov;
.LBB0_251:
	s_andn2_saveexec_b64 s[0:1], s[0:1]
	v_lshl_add_u32 v8, v13, 3, v9
	v_mov_b64_e32 v[10:11], s[40:41]
	s_or_b64 exec, exec, s[0:1]
	v_ashrrev_i32_e32 v9, 31, v8
	v_lshlrev_b64 v[8:9], 21, v[8:9]
	v_lshl_add_u64 v[8:9], v[10:11], 0, v[8:9]
	v_lshlrev_b32_e32 v10, 8, v12
	v_mov_b32_e32 v11, v193
	v_lshl_add_u64 v[8:9], v[8:9], 0, v[10:11]
	v_lshl_add_u64 v[8:9], v[8:9], 0, v[192:193]
	s_waitcnt vmcnt(3)
	global_store_dwordx4 v[8:9], v[4:7], off sc1
	s_nop 1
	v_lshl_or_b32 v5, v44, 2, v19
	v_cmp_lt_i32_e32 vcc, 9, v5
	s_and_saveexec_b64 s[0:1], vcc
	s_xor_b64 s[0:1], exec, s[0:1]
	s_or_saveexec_b64 s[2:3], s[0:1]
	v_and_b32_e32 v8, 0x1fff, v43
	s_xor_b64 exec, exec, s[2:3]
	s_cbranch_execz .LBB0_257
	v_mov_b32_e32 v4, s91
	v_mov_b32_e32 v6, s89
	v_cmp_gt_i32_e64 s[0:1], 8, v5
	v_mov_b32_e32 v23, v193
	v_and_b32_e32 v9, 63, v43
	v_cndmask_b32_e64 v7, v4, v6, s[0:1]
	v_mov_b32_e32 v4, s90
	v_mov_b32_e32 v6, s88
	v_cndmask_b32_e64 v6, v4, v6, s[0:1]
	v_lshl_add_u64 v[6:7], s[8:9], 2, v[6:7]
	v_lshl_add_u64 v[6:7], v[6:7], 0, v[22:23]
	global_load_dwordx4 v[10:13], v[6:7], off
	global_load_dwordx4 v[22:25], v[6:7], off offset:16
	s_waitcnt vmcnt(5)
	v_lshlrev_b32_e32 v6, 16, v0
	v_and_b32_e32 v7, 0xffff0000, v0
	v_lshrrev_b32_e32 v4, 6, v8
	v_lshlrev_b32_e32 v14, 16, v3
	v_and_b32_e32 v15, 0xffff0000, v3
	v_lshlrev_b32_e32 v26, 16, v2
	v_and_b32_e32 v27, 0xffff0000, v2
	v_lshlrev_b32_e32 v2, 16, v1
	v_and_b32_e32 v3, 0xffff0000, v1
	v_pk_mul_f32 v[48:49], v[6:7], v[6:7]
	v_cndmask_b32_e64 v4, v9, v4, s[36:37]
	v_pk_mul_f32 v[46:47], v[2:3], v[2:3]
	v_add_f32_e32 v9, v48, v49
	v_add_f32_e32 v9, v46, v9
	v_pk_mul_f32 v[44:45], v[26:27], v[26:27]
	v_add_f32_e32 v9, v47, v9
	v_add_f32_e32 v9, v44, v9
	v_pk_mul_f32 v[0:1], v[14:15], v[14:15]
	v_add_f32_e32 v9, v45, v9
	v_add_f32_e32 v0, v0, v9
	v_add_f32_e32 v1, v1, v0
	ds_bpermute_b32 v9, v31, v1
	v_cvt_f32_ubyte0_e32 v4, v4
	v_mul_f32_e32 v48, v35, v4
	v_mul_f32_e32 v49, v36, v4
	v_mul_f32_e32 v50, v37, v4
	s_waitcnt lgkmcnt(0)
	v_add_f32_e32 v9, v1, v9
	ds_bpermute_b32 v47, v32, v9
	v_mul_f32_e32 v51, v38, v4
	v_mul_f32_e32 v52, v39, v4
	v_mul_f32_e32 v46, 0.15915494, v48
	v_mul_f32_e32 v48, 0.15915494, v49
	s_waitcnt lgkmcnt(0)
	v_add_f32_e32 v9, v9, v47
	v_mul_f32_e32 v49, 0.15915494, v50
	v_mul_f32_e32 v50, 0.15915494, v51
	v_mul_f32_e32 v51, 0.15915494, v52
	ds_bpermute_b32 v52, v33, v9
	s_mov_b32 s0, 0x800000
	v_mul_f32_e32 v53, v40, v4
	v_mul_f32_e32 v54, v41, v4
	v_mul_f32_e32 v4, v42, v4
	s_waitcnt lgkmcnt(0)
	v_add_f32_e32 v9, v9, v52
	ds_bpermute_b32 v56, v34, v9
	v_mul_f32_e32 v55, 0.15915494, v54
	v_mul_f32_e32 v4, 0.15915494, v4
	v_cos_f32_e32 v54, v55
	v_sin_f32_e32 v57, v4
	s_waitcnt lgkmcnt(0)
	v_add_f32_e32 v9, v9, v56
	v_fmamk_f32 v9, v9, 0x3c000000, v227
	v_mul_f32_e32 v56, 0x4b800000, v9
	v_cmp_gt_f32_e64 s[0:1], s0, v9
	v_sin_f32_e32 v44, v46
	v_sin_f32_e32 v45, v48
	v_cndmask_b32_e64 v9, v9, v56, s[0:1]
	v_rsq_f32_e32 v9, v9
	v_sin_f32_e32 v56, v55
	v_cos_f32_e32 v55, v4
	v_cos_f32_e32 v0, v46
	v_mul_f32_e32 v4, 0x45800000, v9
	v_cndmask_b32_e64 v4, v9, v4, s[0:1]
	v_pk_mul_f32 v[6:7], v[4:5], v[6:7] op_sel_hi:[0,1]
	v_pk_mul_f32 v[2:3], v[4:5], v[2:3] op_sel_hi:[0,1]
	v_cos_f32_e32 v1, v48
	v_cos_f32_e32 v46, v49
	v_sin_f32_e32 v48, v49
	v_sin_f32_e32 v49, v50
	v_cos_f32_e32 v47, v50
	v_mul_f32_e32 v53, 0.15915494, v53
	v_cos_f32_e32 v50, v51
	v_sin_f32_e32 v52, v51
	v_cos_f32_e32 v51, v53
	v_sin_f32_e32 v53, v53
	s_waitcnt vmcnt(1)
	v_pk_mul_f32 v[6:7], v[10:11], v[6:7]
	ds_bpermute_b32 v10, v33, v6
	ds_bpermute_b32 v11, v33, v7
	v_pk_mul_f32 v[2:3], v[12:13], v[2:3]
	ds_bpermute_b32 v12, v33, v2
	ds_bpermute_b32 v13, v33, v3
	s_waitcnt lgkmcnt(2)
	v_pk_mul_f32 v[10:11], v[44:45], v[10:11]
	s_nop 0
	v_cndmask_b32_e64 v11, v11, -v11, s[38:39]
	v_cndmask_b32_e64 v10, v10, -v10, s[38:39]
	v_pk_fma_f32 v[0:1], v[0:1], v[6:7], v[10:11]
	s_waitcnt lgkmcnt(0)
	v_pk_mul_f32 v[6:7], v[48:49], v[12:13]
	v_pk_mul_f32 v[12:13], v[4:5], v[14:15] op_sel_hi:[0,1]
	v_cndmask_b32_e64 v7, v7, -v7, s[38:39]
	v_cndmask_b32_e64 v6, v6, -v6, s[38:39]
	v_pk_fma_f32 v[2:3], v[46:47], v[2:3], v[6:7]
	v_pk_mul_f32 v[6:7], v[4:5], v[26:27] op_sel_hi:[0,1]
	s_waitcnt vmcnt(0)
	v_pk_mul_f32 v[6:7], v[6:7], v[22:23]
	ds_bpermute_b32 v10, v33, v6
	ds_bpermute_b32 v11, v33, v7
	v_pk_mul_f32 v[12:13], v[12:13], v[24:25]
	ds_bpermute_b32 v14, v33, v12
	ds_bpermute_b32 v15, v33, v13
	v_cvt_pk_bf16_f32 v0, v0, v1
	s_waitcnt lgkmcnt(2)
	v_pk_mul_f32 v[10:11], v[52:53], v[10:11]
	v_cvt_pk_bf16_f32 v1, v2, v3
	v_cndmask_b32_e64 v11, v11, -v11, s[38:39]
	v_cndmask_b32_e64 v10, v10, -v10, s[38:39]
	v_pk_fma_f32 v[6:7], v[50:51], v[6:7], v[10:11]
	s_waitcnt lgkmcnt(0)
	v_pk_mul_f32 v[10:11], v[56:57], v[14:15]
	v_cvt_pk_bf16_f32 v2, v6, v7
	v_cndmask_b32_e64 v11, v11, -v11, s[38:39]
	v_cndmask_b32_e64 v10, v10, -v10, s[38:39]
	v_pk_fma_f32 v[10:11], v[54:55], v[12:13], v[10:11]
	s_nop 0
	v_cvt_pk_bf16_f32 v3, v10, v11

; __global__ void __launch_bounds__(512) mega(Args a) {
;     ...
;           bf16_t* dst = hh < 8 ? QBc + ((size_t)(b * 8 + hh) * SEQ + s) * 128 : (hh < 10 ? KBc + ((size_t)(b * 2 + hh - 8) * SEQ + s) * 128 : VBc + ((size_t)(b * 2 + hh - 10) * SEQ + s) * 128);
;           *(u32x4*)(dst + u * 8) = ov;
;         };
;         auto prep_src = [&](const int it) { const int tok = it / 3, hh = (it % 3) * 4 + sb; return (const u32x4*)(PROJ + (size_t)tok * NIN + C_QB + hh * 128 + u * 8); };
;         int it0 = gw;
;         for (; it0 + 3 * NGW < MT * 3; it0 += 4 * NGW) {
;           const u32x4 r0 = *prep_src(it0), r1 = *prep_src(it0 + NGW), r2 = *prep_src(it0 + 2 * NGW), r3 = *prep_src(it0 + 3 * NGW);
;           prep_item(it0, r0); prep_item(it0 + NGW, r1); prep_item(it0 + 2 * NGW, r2); prep_item(it0 + 3 * NGW, r3);
;         }
;         for (; it0 < MT * 3; it0 += NGW) prep_item(it0, *prep_src(it0));
.LBB0_268:
	s_or_b64 exec, exec, s[36:37]
	v_ashrrev_i32_e32 v9, 31, v8
	v_lshlrev_b64 v[8:9], 21, v[8:9]
	v_lshl_add_u64 v[8:9], v[10:11], 0, v[8:9]
	v_lshlrev_b32_e32 v10, 8, v21
	v_mov_b32_e32 v11, v193
	v_add_u32_e32 v17, s16, v17
	s_mov_b32 s19, 0xbfff
	v_lshl_add_u64 v[8:9], v[8:9], 0, v[10:11]
	v_cmp_lt_i32_e32 vcc, s19, v17
	v_lshl_add_u64 v[8:9], v[8:9], 0, v[192:193]
	v_add_u32_e32 v4, s15, v4
	s_or_b64 s[38:39], vcc, s[38:39]
	v_add_u32_e32 v6, s17, v6
	s_waitcnt vmcnt(0)
	global_store_dwordx4 v[8:9], v[0:3], off sc1
	s_andn2_b64 exec, exec, s[38:39]
	s_cbranch_execz .LBB0_279
